# GEMM in-projection phases: accumulators cleared pairwise (v_mov_b64) right after the epilogue's read of each pair, in the shadow of the store-bound epilogue, instead of a 127-instruction run between t
# speedup vs baseline: 1.0477x; 1.0071x over previous
.LBB0_96:
	v_bfe_u32 v18, v10, 4, 2
	v_and_b32_e32 v17, 15, v10
	v_lshlrev_b32_e32 v171, 3, v18
	v_lshlrev_b32_e32 v18, 4, v18
	v_lshlrev_b32_e32 v10, 2, v10
	s_mov_b64 s[40:41], 0x80
	s_and_b32 s5, s5, 3
	s_lshl_b32 s53, s4, 6
	v_lshl_or_b32 v18, v17, 6, v18
	s_lshl_b32 s4, s4, 13
	v_and_b32_e32 v10, 32, v10
	s_add_i32 m0, s19, 0x18000
	v_lshl_add_u64 v[8:9], v[8:9], 0, s[40:41]
	v_bitop3_b32 v19, v18, s4, v10 bitop3:0xde
	s_lshl_b32 s54, s5, 5
	s_lshl_b32 s4, s5, 12
	s_waitcnt vmcnt(2)
	s_barrier
	global_load_lds_dwordx4 v[8:9], off
	v_lshl_add_u64 v[6:7], v[6:7], 0, s[40:41]
	s_add_i32 m0, s19, 0x1a000
	s_add_i32 s55, s19, 0x8000
	s_add_i32 s56, s19, 0xa000
	global_load_lds_dwordx4 v[6:7], off
	v_lshl_add_u64 v[2:3], v[2:3], 0, s[40:41]
	s_mov_b32 m0, s55
	s_add_u32 s36, s8, 0x40080
	global_load_lds_dwordx4 v[2:3], off
	v_lshl_add_u64 v[2:3], v[4:5], 0, s[40:41]
	s_mov_b32 m0, s56
	s_addc_u32 s37, s9, 0
	global_load_lds_dwordx4 v[2:3], off
	s_add_i32 m0, s19, 0x1c000
	v_lshl_add_u64 v[2:3], s[36:37], 0, v[138:139]
	global_load_lds_dwordx4 v[2:3], off
	v_lshl_add_u64 v[2:3], s[36:37], 0, v[140:141]
	s_add_i32 m0, s19, 0x1e000
	v_lshlrev_b32_e32 v146, 7, v17
	global_load_lds_dwordx4 v[2:3], off
	v_lshlrev_b32_e32 v2, 14, v11
	v_and_b32_e32 v2, 0xffff8000, v2
	v_lshl_add_u32 v2, v12, 11, v2
	v_and_b32_e32 v3, 1, v11
	v_lshl_or_b32 v2, v3, 6, v2
	v_lshl_add_u64 v[148:149], s[0:1], 0, v[146:147]
	v_lshl_add_u32 v146, v13, 1, v2
	v_lshlrev_b32_e32 v2, 14, v14
	v_and_b32_e32 v2, 0xffff8000, v2
	v_lshl_add_u32 v2, v15, 11, v2
	v_and_b32_e32 v3, 1, v14
	v_bitop3_b32 v172, v18, s4, v10 bitop3:0xde
	s_mov_b64 s[4:5], 0x40080
	s_waitcnt vmcnt(6)
	v_lshl_or_b32 v2, v3, 6, v2
	v_or_b32_e32 v170, s53, v17
	s_cmpk_lt_u32 s6, 0x100
	s_mov_b64 s[6:7], 0x1000
	s_mov_b64 s[36:37], 0x1800
	v_lshl_add_u64 v[150:151], v[146:147], 0, s[4:5]
	v_lshl_add_u32 v146, v16, 1, v2
	v_or_b32_e32 v174, s54, v171
	s_cselect_b64 s[42:43], -1, 0
	s_add_i32 s57, s53, 0x80
	s_mov_b64 s[44:45], 0x100
	s_add_i32 s58, 0, 0x10000
	s_add_i32 s59, 0, 0x14000
	v_add_u32_e32 v173, 0, v19
	s_mov_b32 s61, 0
	v_mov_b64_e32 v[2:3], 0
	v_mov_b64_e32 v[4:5], 0
	v_mov_b64_e32 v[6:7], 0
	v_mov_b64_e32 v[8:9], 0
	v_mov_b64_e32 v[10:11], 0
	v_mov_b64_e32 v[12:13], 0
	v_mov_b64_e32 v[14:15], 0
	v_mov_b64_e32 v[16:17], 0
	v_mov_b64_e32 v[18:19], 0
	v_mov_b64_e32 v[20:21], 0
	v_mov_b64_e32 v[22:23], 0
	v_mov_b64_e32 v[24:25], 0
	v_mov_b64_e32 v[26:27], 0
	v_mov_b64_e32 v[28:29], 0
	v_mov_b64_e32 v[30:31], 0
	v_mov_b64_e32 v[32:33], 0
	v_mov_b64_e32 v[34:35], 0
	v_mov_b64_e32 v[36:37], 0
	v_mov_b64_e32 v[38:39], 0
	v_mov_b64_e32 v[40:41], 0
	v_mov_b64_e32 v[42:43], 0
	v_mov_b64_e32 v[44:45], 0
	v_mov_b64_e32 v[46:47], 0
	v_mov_b64_e32 v[48:49], 0
	v_mov_b64_e32 v[50:51], 0
	v_mov_b64_e32 v[52:53], 0
	v_mov_b64_e32 v[54:55], 0
	v_mov_b64_e32 v[56:57], 0
	v_mov_b64_e32 v[58:59], 0
	v_mov_b64_e32 v[60:61], 0
	v_mov_b64_e32 v[62:63], 0
	v_mov_b64_e32 v[64:65], 0
	v_mov_b64_e32 v[66:67], 0
	v_mov_b64_e32 v[68:69], 0
	v_mov_b64_e32 v[70:71], 0
	v_mov_b64_e32 v[72:73], 0
	v_mov_b64_e32 v[74:75], 0
	v_mov_b64_e32 v[76:77], 0
	v_mov_b64_e32 v[78:79], 0
	v_mov_b64_e32 v[80:81], 0
	v_mov_b64_e32 v[82:83], 0
	v_mov_b64_e32 v[84:85], 0
	v_mov_b64_e32 v[86:87], 0
	v_mov_b64_e32 v[88:89], 0
	v_mov_b64_e32 v[90:91], 0
	v_mov_b64_e32 v[92:93], 0
	v_mov_b64_e32 v[94:95], 0
	v_mov_b64_e32 v[96:97], 0
	v_mov_b64_e32 v[98:99], 0
	v_mov_b64_e32 v[100:101], 0
	v_mov_b64_e32 v[102:103], 0
	v_mov_b64_e32 v[104:105], 0
	v_mov_b64_e32 v[106:107], 0
	v_mov_b64_e32 v[108:109], 0
	v_mov_b64_e32 v[110:111], 0
	v_mov_b64_e32 v[112:113], 0
	v_mov_b64_e32 v[114:115], 0
	v_mov_b64_e32 v[116:117], 0
	v_mov_b64_e32 v[118:119], 0
	v_mov_b64_e32 v[120:121], 0
	v_mov_b64_e32 v[122:123], 0
	v_mov_b64_e32 v[124:125], 0
	v_mov_b64_e32 v[126:127], 0
	v_mov_b64_e32 v[128:129], 0
	s_mov_b64 s[48:49], s[8:9]
	v_or_b32_e32 v175, 0x80, v174
	v_or_b32_e32 v176, 16, v170
	v_or_b32_e32 v177, 32, v170
	v_or_b32_e32 v178, 48, v170
	v_add_u32_e32 v179, 0x80, v170
	v_add_u32_e32 v180, 0x90, v170
	v_add_u32_e32 v181, 0xa0, v170
	v_add_u32_e32 v182, 0xb0, v170
	v_lshl_add_u64 v[152:153], v[148:149], 0, s[6:7]
	v_lshl_add_u64 v[154:155], v[148:149], 0, s[36:37]
	v_lshl_add_u64 v[156:157], v[146:147], 0, s[4:5]
	v_mov_b64_e32 v[158:159], 0x400
	v_mov_b64_e32 v[160:161], 0x3ff
	s_barrier
	s_branch .LBB0_98
.LBB0_97:
	v_mov_b32_e32 v2, 0
	s_mov_b32 s14, s46
	s_mov_b32 s15, s60
	s_mov_b32 s25, s28
	v_mov_b32_e32 v3, 0
	s_mov_b64 s[26:27], s[50:51]
	s_mov_b32 s61, s62
	s_andn2_b64 vcc, exec, s[4:5]
	s_mov_b64 s[8:9], s[48:49]
	s_cbranch_vccz .LBB0_211

.LBB0_111:
	s_cmp_lg_u32 s25, 0
	s_cselect_b64 s[36:37], -1, 0
	s_and_b64 vcc, exec, s[36:37]
	v_cvt_pk_bf16_f32 v134, v126, v127
	v_mov_b64_e32 v[126:127], 0
	v_cvt_pk_bf16_f32 v135, v128, v129
	v_mov_b64_e32 v[128:129], 0
	v_cvt_pk_bf16_f32 v136, v122, v123
	v_mov_b64_e32 v[122:123], 0
	v_cvt_pk_bf16_f32 v137, v124, v125
	v_mov_b64_e32 v[124:125], 0
	v_cvt_pk_bf16_f32 v130, v94, v95
	v_mov_b64_e32 v[94:95], 0
	v_cvt_pk_bf16_f32 v131, v96, v97
	v_mov_b64_e32 v[96:97], 0
	v_cvt_pk_bf16_f32 v132, v90, v91
	v_mov_b64_e32 v[90:91], 0
	v_cvt_pk_bf16_f32 v133, v92, v93
	v_mov_b64_e32 v[92:93], 0
	s_cbranch_vccz .LBB0_113
	s_lshl_b32 s8, s14, 8
	s_and_b32 s8, s8, 0x300
	s_lshl_b32 s38, s15, 8
	s_add_i32 s8, s8, s53
	s_lshl_b32 s9, s14, 2
	v_or_b32_e32 v146, s38, v174
	s_ashr_i32 s8, s8, 6
	s_and_b32 s9, s9, -16
	v_ashrrev_i32_e32 v162, 31, v146
	s_add_i32 s9, s9, s8
	v_lshrrev_b32_e32 v162, 26, v162
	s_sub_i32 s8, s9, 48
	v_add_u32_e32 v164, v146, v162
	s_ashr_i32 s9, s8, 31
	v_ashrrev_i32_e32 v162, 6, v164
	s_lshl_b64 s[8:9], s[8:9], 8
	v_ashrrev_i32_e32 v163, 31, v162
	v_lshl_add_u64 v[162:163], s[8:9], 0, v[162:163]
	v_and_b32_e32 v164, 0xffffffc0, v164
	v_lshlrev_b64 v[162:163], 13, v[162:163]
	v_sub_u32_e32 v164, v146, v164
	v_lshl_add_u64 v[162:163], v[148:149], 0, v[162:163]
	v_ashrrev_i32_e32 v165, 31, v164
	v_lshl_add_u64 v[162:163], v[164:165], 1, v[162:163]
	v_or_b32_e32 v146, s38, v175
	global_store_dwordx4 v[162:163], v[134:137], off
	v_ashrrev_i32_e32 v162, 31, v146
	v_lshrrev_b32_e32 v162, 26, v162
	v_add_u32_e32 v164, v146, v162
	v_ashrrev_i32_e32 v162, 6, v164
	v_ashrrev_i32_e32 v163, 31, v162
	v_lshl_add_u64 v[162:163], s[8:9], 0, v[162:163]
	v_and_b32_e32 v164, 0xffffffc0, v164
	v_lshlrev_b64 v[162:163], 13, v[162:163]
	v_sub_u32_e32 v164, v146, v164
	v_lshl_add_u64 v[162:163], v[148:149], 0, v[162:163]
	v_ashrrev_i32_e32 v165, 31, v164
	v_lshl_add_u64 v[162:163], v[164:165], 1, v[162:163]
	global_store_dwordx4 v[162:163], v[130:133], off
	s_cbranch_execz .LBB0_114
	s_branch .LBB0_123

.LBB0_123:
	s_nop 1
	v_cndmask_b32_e64 v130, 0, 1, s[36:37]
	v_cmp_ne_u32_e64 s[8:9], 1, v130
	s_andn2_b64 vcc, exec, s[36:37]
	v_cvt_pk_bf16_f32 v134, v118, v119
	v_mov_b64_e32 v[118:119], 0
	v_cvt_pk_bf16_f32 v135, v120, v121
	v_mov_b64_e32 v[120:121], 0
	v_cvt_pk_bf16_f32 v136, v114, v115
	v_mov_b64_e32 v[114:115], 0
	v_cvt_pk_bf16_f32 v137, v116, v117
	v_mov_b64_e32 v[116:117], 0
	v_cvt_pk_bf16_f32 v130, v86, v87
	v_mov_b64_e32 v[86:87], 0
	v_cvt_pk_bf16_f32 v131, v88, v89
	v_mov_b64_e32 v[88:89], 0
	v_cvt_pk_bf16_f32 v132, v82, v83
	v_mov_b64_e32 v[82:83], 0
	v_cvt_pk_bf16_f32 v133, v84, v85
	v_mov_b64_e32 v[84:85], 0
	s_cbranch_vccnz .LBB0_125
	s_lshl_b32 s36, s14, 8
	s_and_b32 s36, s36, 0x300
	s_lshl_b32 s38, s15, 8
	s_add_i32 s36, s36, s53
	s_lshl_b32 s37, s14, 2
	v_or_b32_e32 v146, s38, v174
	s_ashr_i32 s36, s36, 6
	s_and_b32 s37, s37, -16
	v_ashrrev_i32_e32 v162, 31, v146
	s_add_i32 s37, s37, s36
	v_lshrrev_b32_e32 v162, 26, v162
	s_sub_i32 s36, s37, 48
	v_add_u32_e32 v164, v146, v162
	s_ashr_i32 s37, s36, 31
	v_ashrrev_i32_e32 v162, 6, v164
	s_lshl_b64 s[36:37], s[36:37], 8
	v_ashrrev_i32_e32 v163, 31, v162
	v_lshl_add_u64 v[162:163], s[36:37], 0, v[162:163]
	v_and_b32_e32 v164, 0xffffffc0, v164
	v_lshlrev_b64 v[162:163], 13, v[162:163]
	v_sub_u32_e32 v164, v146, v164
	v_lshl_add_u64 v[162:163], v[148:149], 0, v[162:163]
	v_ashrrev_i32_e32 v165, 31, v164
	v_lshl_add_u64 v[162:163], v[164:165], 1, v[162:163]
	v_or_b32_e32 v146, s38, v175
	global_store_dwordx4 v[162:163], v[134:137], off offset:2048
	v_ashrrev_i32_e32 v162, 31, v146
	v_lshrrev_b32_e32 v162, 26, v162
	v_add_u32_e32 v164, v146, v162
	v_ashrrev_i32_e32 v162, 6, v164
	v_ashrrev_i32_e32 v163, 31, v162
	v_lshl_add_u64 v[162:163], s[36:37], 0, v[162:163]
	v_and_b32_e32 v164, 0xffffffc0, v164
	v_lshlrev_b64 v[162:163], 13, v[162:163]
	v_sub_u32_e32 v164, v146, v164
	v_lshl_add_u64 v[162:163], v[148:149], 0, v[162:163]
	v_ashrrev_i32_e32 v165, 31, v164
	v_lshl_add_u64 v[162:163], v[164:165], 1, v[162:163]
	global_store_dwordx4 v[162:163], v[130:133], off offset:2048
	s_cbranch_execz .LBB0_126
	s_branch .LBB0_135

.LBB0_135:
	s_and_b64 vcc, exec, s[8:9]
	v_cvt_pk_bf16_f32 v134, v110, v111
	v_mov_b64_e32 v[110:111], 0
	v_cvt_pk_bf16_f32 v135, v112, v113
	v_mov_b64_e32 v[112:113], 0
	v_cvt_pk_bf16_f32 v136, v106, v107
	v_mov_b64_e32 v[106:107], 0
	v_cvt_pk_bf16_f32 v137, v108, v109
	v_mov_b64_e32 v[108:109], 0
	v_cvt_pk_bf16_f32 v130, v78, v79
	v_mov_b64_e32 v[78:79], 0
	v_cvt_pk_bf16_f32 v131, v80, v81
	v_mov_b64_e32 v[80:81], 0
	v_cvt_pk_bf16_f32 v132, v74, v75
	v_mov_b64_e32 v[74:75], 0
	v_cvt_pk_bf16_f32 v133, v76, v77
	v_mov_b64_e32 v[76:77], 0
	s_cbranch_vccnz .LBB0_137
	s_lshl_b32 s36, s14, 8
	s_and_b32 s36, s36, 0x300
	s_lshl_b32 s38, s15, 8
	s_add_i32 s36, s36, s53
	s_lshl_b32 s37, s14, 2
	v_or_b32_e32 v146, s38, v174
	s_ashr_i32 s36, s36, 6
	s_and_b32 s37, s37, -16
	v_ashrrev_i32_e32 v162, 31, v146
	s_add_i32 s37, s37, s36
	v_lshrrev_b32_e32 v162, 26, v162
	s_sub_i32 s36, s37, 48
	v_add_u32_e32 v164, v146, v162
	s_ashr_i32 s37, s36, 31
	v_ashrrev_i32_e32 v162, 6, v164
	s_lshl_b64 s[36:37], s[36:37], 8
	v_ashrrev_i32_e32 v163, 31, v162
	v_lshl_add_u64 v[162:163], s[36:37], 0, v[162:163]
	v_and_b32_e32 v164, 0xffffffc0, v164
	v_lshlrev_b64 v[162:163], 13, v[162:163]
	v_sub_u32_e32 v164, v146, v164
	v_lshl_add_u64 v[162:163], v[152:153], 0, v[162:163]
	v_ashrrev_i32_e32 v165, 31, v164
	v_lshl_add_u64 v[162:163], v[164:165], 1, v[162:163]
	v_or_b32_e32 v146, s38, v175
	global_store_dwordx4 v[162:163], v[134:137], off
	v_ashrrev_i32_e32 v162, 31, v146
	v_lshrrev_b32_e32 v162, 26, v162
	v_add_u32_e32 v164, v146, v162
	v_ashrrev_i32_e32 v162, 6, v164
	v_ashrrev_i32_e32 v163, 31, v162
	v_lshl_add_u64 v[162:163], s[36:37], 0, v[162:163]
	v_and_b32_e32 v164, 0xffffffc0, v164
	v_lshlrev_b64 v[162:163], 13, v[162:163]
	v_sub_u32_e32 v164, v146, v164
	v_lshl_add_u64 v[162:163], v[152:153], 0, v[162:163]
	v_ashrrev_i32_e32 v165, 31, v164
	v_lshl_add_u64 v[162:163], v[164:165], 1, v[162:163]
	global_store_dwordx4 v[162:163], v[130:133], off
	s_cbranch_execz .LBB0_138
	s_branch .LBB0_147

.LBB0_147:
	s_and_b64 vcc, exec, s[8:9]
	v_cvt_pk_bf16_f32 v134, v102, v103
	v_mov_b64_e32 v[102:103], 0
	v_cvt_pk_bf16_f32 v135, v104, v105
	v_mov_b64_e32 v[104:105], 0
	v_cvt_pk_bf16_f32 v136, v98, v99
	v_mov_b64_e32 v[98:99], 0
	v_cvt_pk_bf16_f32 v137, v100, v101
	v_mov_b64_e32 v[100:101], 0
	v_cvt_pk_bf16_f32 v130, v70, v71
	v_mov_b64_e32 v[70:71], 0
	v_cvt_pk_bf16_f32 v131, v72, v73
	v_mov_b64_e32 v[72:73], 0
	v_cvt_pk_bf16_f32 v132, v66, v67
	v_mov_b64_e32 v[66:67], 0
	v_cvt_pk_bf16_f32 v133, v68, v69
	v_mov_b64_e32 v[68:69], 0
	s_cbranch_vccnz .LBB0_149
	s_lshl_b32 s36, s14, 8
	s_and_b32 s36, s36, 0x300
	s_lshl_b32 s38, s15, 8
	s_add_i32 s36, s36, s53
	s_lshl_b32 s37, s14, 2
	v_or_b32_e32 v146, s38, v174
	s_ashr_i32 s36, s36, 6
	s_and_b32 s37, s37, -16
	v_ashrrev_i32_e32 v162, 31, v146
	s_add_i32 s37, s37, s36
	v_lshrrev_b32_e32 v162, 26, v162
	s_sub_i32 s36, s37, 48
	v_add_u32_e32 v164, v146, v162
	s_ashr_i32 s37, s36, 31
	v_ashrrev_i32_e32 v162, 6, v164
	s_lshl_b64 s[36:37], s[36:37], 8
	v_ashrrev_i32_e32 v163, 31, v162
	v_lshl_add_u64 v[162:163], s[36:37], 0, v[162:163]
	v_and_b32_e32 v164, 0xffffffc0, v164
	v_lshlrev_b64 v[162:163], 13, v[162:163]
	v_sub_u32_e32 v164, v146, v164
	v_lshl_add_u64 v[162:163], v[154:155], 0, v[162:163]
	v_ashrrev_i32_e32 v165, 31, v164
	v_lshl_add_u64 v[162:163], v[164:165], 1, v[162:163]
	v_or_b32_e32 v146, s38, v175
	global_store_dwordx4 v[162:163], v[134:137], off
	v_ashrrev_i32_e32 v162, 31, v146
	v_lshrrev_b32_e32 v162, 26, v162
	v_add_u32_e32 v164, v146, v162
	v_ashrrev_i32_e32 v162, 6, v164
	v_ashrrev_i32_e32 v163, 31, v162
	v_lshl_add_u64 v[162:163], s[36:37], 0, v[162:163]
	v_and_b32_e32 v164, 0xffffffc0, v164
	v_lshlrev_b64 v[162:163], 13, v[162:163]
	v_sub_u32_e32 v164, v146, v164
	v_lshl_add_u64 v[162:163], v[154:155], 0, v[162:163]
	v_ashrrev_i32_e32 v165, 31, v164
	v_lshl_add_u64 v[162:163], v[164:165], 1, v[162:163]
	global_store_dwordx4 v[162:163], v[130:133], off
	s_cbranch_execz .LBB0_150
	s_branch .LBB0_159

.LBB0_159:
	s_and_b64 vcc, exec, s[8:9]
	v_cvt_pk_bf16_f32 v134, v62, v63
	v_mov_b64_e32 v[62:63], 0
	v_cvt_pk_bf16_f32 v135, v64, v65
	v_mov_b64_e32 v[64:65], 0
	v_cvt_pk_bf16_f32 v136, v58, v59
	v_mov_b64_e32 v[58:59], 0
	v_cvt_pk_bf16_f32 v137, v60, v61
	v_mov_b64_e32 v[60:61], 0
	v_cvt_pk_bf16_f32 v130, v30, v31
	v_mov_b64_e32 v[30:31], 0
	v_cvt_pk_bf16_f32 v131, v32, v33
	v_mov_b64_e32 v[32:33], 0
	v_cvt_pk_bf16_f32 v132, v26, v27
	v_mov_b64_e32 v[26:27], 0
	v_cvt_pk_bf16_f32 v133, v28, v29
	v_mov_b64_e32 v[28:29], 0
	s_cbranch_vccnz .LBB0_161
	s_lshl_b32 s36, s14, 8
	s_and_b32 s36, s36, 0x300
	s_lshl_b32 s38, s15, 8
	s_add_i32 s36, s36, s57
	s_lshl_b32 s37, s14, 2
	v_or_b32_e32 v146, s38, v174
	s_ashr_i32 s36, s36, 6
	s_and_b32 s37, s37, -16
	v_ashrrev_i32_e32 v162, 31, v146
	s_add_i32 s37, s37, s36
	v_lshrrev_b32_e32 v162, 26, v162
	s_sub_i32 s36, s37, 48
	v_add_u32_e32 v164, v146, v162
	s_ashr_i32 s37, s36, 31
	v_ashrrev_i32_e32 v162, 6, v164
	s_lshl_b64 s[36:37], s[36:37], 8
	v_ashrrev_i32_e32 v163, 31, v162
	v_lshl_add_u64 v[162:163], s[36:37], 0, v[162:163]
	v_and_b32_e32 v164, 0xffffffc0, v164
	v_lshlrev_b64 v[162:163], 13, v[162:163]
	v_sub_u32_e32 v164, v146, v164
	v_lshl_add_u64 v[162:163], v[148:149], 0, v[162:163]
	v_ashrrev_i32_e32 v165, 31, v164
	v_lshl_add_u64 v[162:163], v[164:165], 1, v[162:163]
	v_or_b32_e32 v146, s38, v175
	global_store_dwordx4 v[162:163], v[134:137], off
	v_ashrrev_i32_e32 v162, 31, v146
	v_lshrrev_b32_e32 v162, 26, v162
	v_add_u32_e32 v164, v146, v162
	v_ashrrev_i32_e32 v162, 6, v164
	v_ashrrev_i32_e32 v163, 31, v162
	v_lshl_add_u64 v[162:163], s[36:37], 0, v[162:163]
	v_and_b32_e32 v164, 0xffffffc0, v164
	v_lshlrev_b64 v[162:163], 13, v[162:163]
	v_sub_u32_e32 v164, v146, v164
	v_lshl_add_u64 v[162:163], v[148:149], 0, v[162:163]
	v_ashrrev_i32_e32 v165, 31, v164
	v_lshl_add_u64 v[162:163], v[164:165], 1, v[162:163]
	global_store_dwordx4 v[162:163], v[130:133], off
	s_cbranch_execz .LBB0_162
	s_branch .LBB0_171

.LBB0_171:
	s_and_b64 vcc, exec, s[8:9]
	v_cvt_pk_bf16_f32 v134, v54, v55
	v_mov_b64_e32 v[54:55], 0
	v_cvt_pk_bf16_f32 v135, v56, v57
	v_mov_b64_e32 v[56:57], 0
	v_cvt_pk_bf16_f32 v136, v50, v51
	v_mov_b64_e32 v[50:51], 0
	v_cvt_pk_bf16_f32 v137, v52, v53
	v_mov_b64_e32 v[52:53], 0
	v_cvt_pk_bf16_f32 v130, v22, v23
	v_mov_b64_e32 v[22:23], 0
	v_cvt_pk_bf16_f32 v131, v24, v25
	v_mov_b64_e32 v[24:25], 0
	v_cvt_pk_bf16_f32 v132, v18, v19
	v_mov_b64_e32 v[18:19], 0
	v_cvt_pk_bf16_f32 v133, v20, v21
	v_mov_b64_e32 v[20:21], 0
	s_cbranch_vccnz .LBB0_173
	s_lshl_b32 s36, s14, 8
	s_and_b32 s36, s36, 0x300
	s_lshl_b32 s38, s15, 8
	s_add_i32 s36, s36, s57
	s_lshl_b32 s37, s14, 2
	v_or_b32_e32 v146, s38, v174
	s_ashr_i32 s36, s36, 6
	s_and_b32 s37, s37, -16
	v_ashrrev_i32_e32 v162, 31, v146
	s_add_i32 s37, s37, s36
	v_lshrrev_b32_e32 v162, 26, v162
	s_sub_i32 s36, s37, 48
	v_add_u32_e32 v164, v146, v162
	s_ashr_i32 s37, s36, 31
	v_ashrrev_i32_e32 v162, 6, v164
	s_lshl_b64 s[36:37], s[36:37], 8
	v_ashrrev_i32_e32 v163, 31, v162
	v_lshl_add_u64 v[162:163], s[36:37], 0, v[162:163]
	v_and_b32_e32 v164, 0xffffffc0, v164
	v_lshlrev_b64 v[162:163], 13, v[162:163]
	v_sub_u32_e32 v164, v146, v164
	v_lshl_add_u64 v[162:163], v[148:149], 0, v[162:163]
	v_ashrrev_i32_e32 v165, 31, v164
	v_lshl_add_u64 v[162:163], v[164:165], 1, v[162:163]
	v_or_b32_e32 v146, s38, v175
	global_store_dwordx4 v[162:163], v[134:137], off offset:2048
	v_ashrrev_i32_e32 v162, 31, v146
	v_lshrrev_b32_e32 v162, 26, v162
	v_add_u32_e32 v164, v146, v162
	v_ashrrev_i32_e32 v162, 6, v164
	v_ashrrev_i32_e32 v163, 31, v162
	v_lshl_add_u64 v[162:163], s[36:37], 0, v[162:163]
	v_and_b32_e32 v164, 0xffffffc0, v164
	v_lshlrev_b64 v[162:163], 13, v[162:163]
	v_sub_u32_e32 v164, v146, v164
	v_lshl_add_u64 v[162:163], v[148:149], 0, v[162:163]
	v_ashrrev_i32_e32 v165, 31, v164
	v_lshl_add_u64 v[162:163], v[164:165], 1, v[162:163]
	global_store_dwordx4 v[162:163], v[130:133], off offset:2048
	s_cbranch_execz .LBB0_174
	s_branch .LBB0_183

.LBB0_183:
	s_and_b64 vcc, exec, s[8:9]
	v_cvt_pk_bf16_f32 v134, v46, v47
	v_mov_b64_e32 v[46:47], 0
	v_cvt_pk_bf16_f32 v135, v48, v49
	v_mov_b64_e32 v[48:49], 0
	v_cvt_pk_bf16_f32 v136, v42, v43
	v_mov_b64_e32 v[42:43], 0
	v_cvt_pk_bf16_f32 v137, v44, v45
	v_mov_b64_e32 v[44:45], 0
	v_cvt_pk_bf16_f32 v130, v14, v15
	v_mov_b64_e32 v[14:15], 0
	v_cvt_pk_bf16_f32 v131, v16, v17
	v_mov_b64_e32 v[16:17], 0
	v_cvt_pk_bf16_f32 v132, v10, v11
	v_mov_b64_e32 v[10:11], 0
	v_cvt_pk_bf16_f32 v133, v12, v13
	v_mov_b64_e32 v[12:13], 0
	s_cbranch_vccnz .LBB0_185
	s_lshl_b32 s36, s14, 8
	s_and_b32 s36, s36, 0x300
	s_lshl_b32 s38, s15, 8
	s_add_i32 s36, s36, s57
	s_lshl_b32 s37, s14, 2
	v_or_b32_e32 v146, s38, v174
	s_ashr_i32 s36, s36, 6
	s_and_b32 s37, s37, -16
	v_ashrrev_i32_e32 v162, 31, v146
	s_add_i32 s37, s37, s36
	v_lshrrev_b32_e32 v162, 26, v162
	s_sub_i32 s36, s37, 48
	v_add_u32_e32 v164, v146, v162
	s_ashr_i32 s37, s36, 31
	v_ashrrev_i32_e32 v162, 6, v164
	s_lshl_b64 s[36:37], s[36:37], 8
	v_ashrrev_i32_e32 v163, 31, v162
	v_lshl_add_u64 v[162:163], s[36:37], 0, v[162:163]
	v_and_b32_e32 v164, 0xffffffc0, v164
	v_lshlrev_b64 v[162:163], 13, v[162:163]
	v_sub_u32_e32 v164, v146, v164
	v_lshl_add_u64 v[162:163], v[152:153], 0, v[162:163]
	v_ashrrev_i32_e32 v165, 31, v164
	v_lshl_add_u64 v[162:163], v[164:165], 1, v[162:163]
	v_or_b32_e32 v146, s38, v175
	global_store_dwordx4 v[162:163], v[134:137], off
	v_ashrrev_i32_e32 v162, 31, v146
	v_lshrrev_b32_e32 v162, 26, v162
	v_add_u32_e32 v164, v146, v162
	v_ashrrev_i32_e32 v162, 6, v164
	v_ashrrev_i32_e32 v163, 31, v162
	v_lshl_add_u64 v[162:163], s[36:37], 0, v[162:163]
	v_and_b32_e32 v164, 0xffffffc0, v164
	v_lshlrev_b64 v[162:163], 13, v[162:163]
	v_sub_u32_e32 v164, v146, v164
	v_lshl_add_u64 v[162:163], v[152:153], 0, v[162:163]
	v_ashrrev_i32_e32 v165, 31, v164
	v_lshl_add_u64 v[162:163], v[164:165], 1, v[162:163]
	global_store_dwordx4 v[162:163], v[130:133], off
	s_cbranch_execz .LBB0_186
	s_branch .LBB0_195

.LBB0_195:
	s_and_b64 vcc, exec, s[8:9]
	v_cvt_pk_bf16_f32 v134, v38, v39
	v_mov_b64_e32 v[38:39], 0
	v_cvt_pk_bf16_f32 v135, v40, v41
	v_mov_b64_e32 v[40:41], 0
	v_cvt_pk_bf16_f32 v136, v34, v35
	v_mov_b64_e32 v[34:35], 0
	v_cvt_pk_bf16_f32 v137, v36, v37
	v_mov_b64_e32 v[36:37], 0
	v_cvt_pk_bf16_f32 v130, v6, v7
	v_mov_b64_e32 v[6:7], 0
	v_cvt_pk_bf16_f32 v131, v8, v9
	v_mov_b64_e32 v[8:9], 0
	v_cvt_pk_bf16_f32 v132, v2, v3
	v_mov_b64_e32 v[2:3], 0
	v_cvt_pk_bf16_f32 v133, v4, v5
	v_mov_b64_e32 v[4:5], 0
	s_cbranch_vccnz .LBB0_207
	s_lshl_b32 s8, s14, 8
	s_and_b32 s8, s8, 0x300
	s_lshl_b32 s36, s15, 8
	s_add_i32 s8, s8, s57
	s_lshl_b32 s9, s14, 2
	v_or_b32_e32 v146, s36, v174
	s_ashr_i32 s8, s8, 6
	s_and_b32 s9, s9, -16
	v_ashrrev_i32_e32 v162, 31, v146
	s_add_i32 s9, s9, s8
	v_lshrrev_b32_e32 v162, 26, v162
	s_sub_i32 s8, s9, 48
	v_add_u32_e32 v164, v146, v162
	s_ashr_i32 s9, s8, 31
	v_ashrrev_i32_e32 v162, 6, v164
	s_lshl_b64 s[8:9], s[8:9], 8
	v_ashrrev_i32_e32 v163, 31, v162
	v_lshl_add_u64 v[162:163], s[8:9], 0, v[162:163]
	v_and_b32_e32 v164, 0xffffffc0, v164
	v_lshlrev_b64 v[162:163], 13, v[162:163]
	v_sub_u32_e32 v164, v146, v164
	v_lshl_add_u64 v[162:163], v[154:155], 0, v[162:163]
	v_ashrrev_i32_e32 v165, 31, v164
	v_lshl_add_u64 v[162:163], v[164:165], 1, v[162:163]
	v_or_b32_e32 v146, s36, v175
	global_store_dwordx4 v[162:163], v[134:137], off
	v_ashrrev_i32_e32 v162, 31, v146
	v_lshrrev_b32_e32 v162, 26, v162
	v_add_u32_e32 v164, v146, v162
	v_ashrrev_i32_e32 v162, 6, v164
	v_ashrrev_i32_e32 v163, 31, v162
	v_lshl_add_u64 v[162:163], s[8:9], 0, v[162:163]
	v_and_b32_e32 v164, 0xffffffc0, v164
	v_lshlrev_b64 v[162:163], 13, v[162:163]
	v_sub_u32_e32 v164, v146, v164
	v_lshl_add_u64 v[162:163], v[154:155], 0, v[162:163]
	v_ashrrev_i32_e32 v165, 31, v164
	v_lshl_add_u64 v[162:163], v[164:165], 1, v[162:163]
	global_store_dwordx4 v[162:163], v[130:133], off
	s_cbranch_execnz .LBB0_208

.LBB0_385:
	v_and_b32_e32 v16, 15, v1
	v_and_b32_e32 v17, 48, v1
	v_lshl_or_b32 v194, s4, 6, v16
	v_lshl_or_b32 v16, v16, 6, v17
	v_lshlrev_b32_e32 v17, 2, v1
	s_mov_b64 s[22:23], 0x80
	s_and_b32 s9, s14, 3
	s_lshl_b32 s4, s4, 13
	v_and_b32_e32 v17, 32, v17
	s_add_i32 m0, s20, 0x18000
	v_lshl_add_u64 v[8:9], v[8:9], 0, s[22:23]
	v_bitop3_b32 v18, v16, s4, v17 bitop3:0xde
	s_lshl_b32 s4, s9, 12
	s_waitcnt vmcnt(2)
	s_barrier
	global_load_lds_dwordx4 v[8:9], off
	v_lshl_add_u64 v[6:7], v[6:7], 0, s[22:23]
	s_add_i32 m0, s20, 0x1a000
	s_add_i32 s41, s20, 0x8000
	s_add_i32 s42, s20, 0xa000
	global_load_lds_dwordx4 v[6:7], off
	v_lshl_add_u64 v[4:5], v[4:5], 0, s[22:23]
	s_mov_b32 m0, s41
	s_add_u32 s6, s30, 0x40080
	global_load_lds_dwordx4 v[4:5], off
	v_lshl_add_u64 v[2:3], v[2:3], 0, s[22:23]
	s_mov_b32 m0, s42
	s_addc_u32 s7, s31, 0
	global_load_lds_dwordx4 v[2:3], off
	s_add_i32 m0, s20, 0x1c000
	v_lshl_add_u64 v[2:3], s[6:7], 0, v[130:131]
	global_load_lds_dwordx4 v[2:3], off
	v_lshl_add_u64 v[2:3], s[6:7], 0, v[132:133]
	s_add_i32 m0, s20, 0x1e000
	v_bitop3_b32 v150, v16, s4, v17 bitop3:0xde
	global_load_lds_dwordx4 v[2:3], off
	v_lshlrev_b32_e32 v2, 14, v13
	v_and_b32_e32 v2, 0xffff8000, v2
	v_lshl_add_u32 v2, v14, 11, v2
	v_and_b32_e32 v3, 1, v13
	v_lshl_or_b32 v2, v3, 6, v2
	s_mov_b64 s[4:5], 0x40080
	v_lshl_add_u32 v2, v15, 1, v2
	v_mov_b32_e32 v3, v131
	v_lshl_add_u64 v[138:139], v[2:3], 0, s[4:5]
	v_lshlrev_b32_e32 v2, 14, v10
	v_and_b32_e32 v2, 0xffff8000, v2
	v_lshl_add_u32 v2, v11, 11, v2
	v_and_b32_e32 v3, 1, v10
	s_waitcnt vmcnt(6)
	v_lshl_or_b32 v2, v3, 6, v2
	v_lshl_add_u32 v2, v12, 1, v2
	v_mov_b32_e32 v3, v131
	s_sext_i32_i8 s0, s0
	v_lshl_add_u64 v[140:141], v[2:3], 0, s[4:5]
	v_mov_b64_e32 v[142:143], 0x100
	v_mov_b64_e32 v[144:145], 0xff
	s_add_i32 s43, 0, 0x10000
	s_add_i32 s44, 0, 0x14000
	v_add_u32_e32 v151, 0, v18
	v_mov_b32_e32 v2, 0
	v_mov_b64_e32 v[4:5], 0
	v_mov_b64_e32 v[6:7], 0
	v_mov_b64_e32 v[8:9], 0
	v_mov_b64_e32 v[10:11], 0
	v_mov_b64_e32 v[12:13], 0
	v_mov_b64_e32 v[14:15], 0
	v_mov_b64_e32 v[16:17], 0
	v_mov_b64_e32 v[18:19], 0
	v_mov_b64_e32 v[20:21], 0
	v_mov_b64_e32 v[22:23], 0
	v_mov_b64_e32 v[24:25], 0
	v_mov_b64_e32 v[26:27], 0
	v_mov_b64_e32 v[28:29], 0
	v_mov_b64_e32 v[30:31], 0
	v_mov_b64_e32 v[32:33], 0
	v_mov_b64_e32 v[34:35], 0
	v_mov_b64_e32 v[36:37], 0
	v_mov_b64_e32 v[38:39], 0
	v_mov_b64_e32 v[40:41], 0
	v_mov_b64_e32 v[42:43], 0
	v_mov_b64_e32 v[44:45], 0
	v_mov_b64_e32 v[46:47], 0
	v_mov_b64_e32 v[48:49], 0
	v_mov_b64_e32 v[50:51], 0
	v_mov_b64_e32 v[52:53], 0
	v_mov_b64_e32 v[54:55], 0
	v_mov_b64_e32 v[56:57], 0
	v_mov_b64_e32 v[58:59], 0
	v_mov_b64_e32 v[60:61], 0
	v_mov_b64_e32 v[62:63], 0
	v_mov_b64_e32 v[64:65], 0
	v_mov_b64_e32 v[66:67], 0
	v_mov_b64_e32 v[68:69], 0
	v_mov_b64_e32 v[70:71], 0
	v_mov_b64_e32 v[72:73], 0
	v_mov_b64_e32 v[74:75], 0
	v_mov_b64_e32 v[76:77], 0
	v_mov_b64_e32 v[78:79], 0
	v_mov_b64_e32 v[80:81], 0
	v_mov_b64_e32 v[82:83], 0
	v_mov_b64_e32 v[84:85], 0
	v_mov_b64_e32 v[86:87], 0
	v_mov_b64_e32 v[88:89], 0
	v_mov_b64_e32 v[90:91], 0
	v_mov_b64_e32 v[92:93], 0
	v_mov_b64_e32 v[94:95], 0
	v_mov_b64_e32 v[96:97], 0
	v_mov_b64_e32 v[98:99], 0
	v_mov_b64_e32 v[100:101], 0
	v_mov_b64_e32 v[102:103], 0
	v_mov_b64_e32 v[104:105], 0
	v_mov_b64_e32 v[106:107], 0
	v_mov_b64_e32 v[108:109], 0
	v_mov_b64_e32 v[110:111], 0
	v_mov_b64_e32 v[112:113], 0
	v_mov_b64_e32 v[114:115], 0
	v_mov_b64_e32 v[116:117], 0
	v_mov_b64_e32 v[118:119], 0
	v_mov_b64_e32 v[120:121], 0
	v_mov_b64_e32 v[122:123], 0
	v_mov_b64_e32 v[124:125], 0
	v_mov_b64_e32 v[126:127], 0
	v_mov_b64_e32 v[128:129], 0
	s_mov_b64 s[26:27], s[30:31]
	s_barrier
	s_branch .LBB0_388

.Lprio_g2_done:
.LBB0_395:
	v_add_u32_e32 v164, s43, v150
	v_add_u32_e32 v180, s44, v150
	s_add_u32 s36, s10, s30
	ds_read_b128 v[152:155], v164
	ds_read_b128 v[156:159], v164 offset:1024
	ds_read_b128 v[160:163], v164 offset:2048
	ds_read_b128 v[164:167], v164 offset:3072
	ds_read_b128 v[168:171], v180
	ds_read_b128 v[172:175], v180 offset:1024
	ds_read_b128 v[176:179], v180 offset:2048
	ds_read_b128 v[180:183], v180 offset:3072
	s_addc_u32 s37, s11, s31
	s_add_u32 s36, s36, 0x100
	s_addc_u32 s37, s37, 0
	s_add_u32 s50, s25, s30
	s_addc_u32 s51, s48, s31
	s_cmpk_eq_i32 s30, 0x700
	s_cselect_b32 s39, s29, s37
	s_cselect_b32 s38, s28, s36
	s_cselect_b32 s37, s27, s51
	s_cselect_b32 s36, s26, s50
	v_lshl_add_u64 v[192:193], v[146:147], 0, s[30:31]
	s_add_i32 m0, s20, 0xc000
	ds_read_b128 v[184:187], v151
	ds_read_b128 v[188:191], v151 offset:1024
	ds_read_b128 v[196:199], v151 offset:2048
	ds_read_b128 v[200:203], v151 offset:3072
	ds_read_b128 v[204:207], v151 offset:4096
	ds_read_b128 v[208:211], v151 offset:5120
	ds_read_b128 v[212:215], v151 offset:6144
	ds_read_b128 v[216:219], v151 offset:7168
	global_load_lds_dwordx4 v[192:193], off
	v_lshl_add_u64 v[192:193], v[148:149], 0, s[30:31]
	s_add_i32 m0, s20, 0xe000
	s_nop 0
	global_load_lds_dwordx4 v[192:193], off
	s_waitcnt vmcnt(8)
	s_waitcnt lgkmcnt(0)
	s_barrier
	s_waitcnt lgkmcnt(0)
	v_mfma_f32_16x16x32_bf16 v[126:129], v[152:155], v[184:187], v[126:129]
	v_mfma_f32_16x16x32_bf16 v[122:125], v[160:163], v[184:187], v[122:125]
	v_mfma_f32_16x16x32_bf16 v[118:121], v[152:155], v[196:199], v[118:121]
	v_mfma_f32_16x16x32_bf16 v[114:117], v[160:163], v[196:199], v[114:117]
	v_mfma_f32_16x16x32_bf16 v[110:113], v[152:155], v[204:207], v[110:113]
	v_mfma_f32_16x16x32_bf16 v[102:105], v[160:163], v[204:207], v[102:105]
	v_mfma_f32_16x16x32_bf16 v[94:97], v[152:155], v[212:215], v[94:97]
	v_mfma_f32_16x16x32_bf16 v[86:89], v[160:163], v[212:215], v[86:89]
	v_mfma_f32_16x16x32_bf16 v[126:129], v[156:159], v[188:191], v[126:129]
	v_mfma_f32_16x16x32_bf16 v[122:125], v[164:167], v[188:191], v[122:125]
	v_mfma_f32_16x16x32_bf16 v[118:121], v[156:159], v[200:203], v[118:121]
	v_mfma_f32_16x16x32_bf16 v[114:117], v[164:167], v[200:203], v[114:117]
	v_mfma_f32_16x16x32_bf16 v[110:113], v[156:159], v[208:211], v[110:113]
	v_mfma_f32_16x16x32_bf16 v[102:105], v[164:167], v[208:211], v[102:105]
	v_mfma_f32_16x16x32_bf16 v[94:97], v[156:159], v[216:219], v[94:97]
	v_mfma_f32_16x16x32_bf16 v[86:89], v[164:167], v[216:219], v[86:89]
	v_mfma_f32_16x16x32_bf16 v[106:109], v[168:171], v[184:187], v[106:109]
	v_mfma_f32_16x16x32_bf16 v[98:101], v[176:179], v[184:187], v[98:101]
	v_mfma_f32_16x16x32_bf16 v[90:93], v[168:171], v[196:199], v[90:93]
	v_mfma_f32_16x16x32_bf16 v[82:85], v[176:179], v[196:199], v[82:85]
	v_mfma_f32_16x16x32_bf16 v[78:81], v[168:171], v[204:207], v[78:81]
	v_mfma_f32_16x16x32_bf16 v[74:77], v[176:179], v[204:207], v[74:77]
	v_mfma_f32_16x16x32_bf16 v[70:73], v[168:171], v[212:215], v[70:73]
	v_mfma_f32_16x16x32_bf16 v[66:69], v[176:179], v[212:215], v[66:69]
	v_mfma_f32_16x16x32_bf16 v[106:109], v[172:175], v[188:191], v[106:109]
	v_mfma_f32_16x16x32_bf16 v[98:101], v[180:183], v[188:191], v[98:101]
	v_mfma_f32_16x16x32_bf16 v[90:93], v[172:175], v[200:203], v[90:93]
	v_mfma_f32_16x16x32_bf16 v[82:85], v[180:183], v[200:203], v[82:85]
	v_mfma_f32_16x16x32_bf16 v[78:81], v[172:175], v[208:211], v[78:81]
	v_mfma_f32_16x16x32_bf16 v[74:77], v[180:183], v[208:211], v[74:77]
	v_mfma_f32_16x16x32_bf16 v[70:73], v[172:175], v[216:219], v[70:73]
	v_mfma_f32_16x16x32_bf16 v[66:69], v[180:183], v[216:219], v[66:69]
	s_barrier
	s_add_i32 s50, s43, s15
	v_lshl_add_u64 v[192:193], s[36:37], 0, v[130:131]
	s_mov_b32 m0, s50
	ds_read_b128 v[184:187], v151 offset:16384
	ds_read_b128 v[188:191], v151 offset:17408
	ds_read_b128 v[196:199], v151 offset:18432
	ds_read_b128 v[200:203], v151 offset:19456
	ds_read_b128 v[204:207], v151 offset:20480
	ds_read_b128 v[208:211], v151 offset:21504
	ds_read_b128 v[212:215], v151 offset:22528
	ds_read_b128 v[216:219], v151 offset:23552
	global_load_lds_dwordx4 v[192:193], off
	s_add_i32 m0, s50, 0x2000
	s_add_u32 s50, s36, 0x40000
	v_lshl_add_u64 v[220:221], s[36:37], 0, v[132:133]
	s_addc_u32 s51, s37, 0
	s_add_i32 s53, s44, s15
	global_load_lds_dwordx4 v[220:221], off
	v_lshl_add_u64 v[222:223], s[50:51], 0, v[130:131]
	s_mov_b32 m0, s53
	v_lshl_add_u64 v[224:225], s[38:39], 0, v[136:137]
	global_load_lds_dwordx4 v[222:223], off
	v_lshl_add_u64 v[222:223], s[50:51], 0, v[132:133]
	s_add_i32 m0, s53, 0x2000
	s_nop 0
	global_load_lds_dwordx4 v[222:223], off
	v_lshl_add_u64 v[222:223], s[38:39], 0, v[134:135]
	s_mov_b32 m0, s20
	s_nop 0
	global_load_lds_dwordx4 v[222:223], off
	s_mov_b32 m0, s21
	s_nop 0
	global_load_lds_dwordx4 v[224:225], off
	s_waitcnt vmcnt(8)
	s_waitcnt lgkmcnt(0)
	s_barrier
	s_waitcnt lgkmcnt(0)
	v_mfma_f32_16x16x32_bf16 v[62:65], v[152:155], v[184:187], v[62:65]
	v_mfma_f32_16x16x32_bf16 v[58:61], v[160:163], v[184:187], v[58:61]
	v_mfma_f32_16x16x32_bf16 v[54:57], v[152:155], v[196:199], v[54:57]
	v_mfma_f32_16x16x32_bf16 v[50:53], v[160:163], v[196:199], v[50:53]
	v_mfma_f32_16x16x32_bf16 v[46:49], v[152:155], v[204:207], v[46:49]
	v_mfma_f32_16x16x32_bf16 v[38:41], v[160:163], v[204:207], v[38:41]
	v_mfma_f32_16x16x32_bf16 v[30:33], v[152:155], v[212:215], v[30:33]
	v_mfma_f32_16x16x32_bf16 v[22:25], v[160:163], v[212:215], v[22:25]
	v_mfma_f32_16x16x32_bf16 v[62:65], v[156:159], v[188:191], v[62:65]
	v_mfma_f32_16x16x32_bf16 v[58:61], v[164:167], v[188:191], v[58:61]
	v_mfma_f32_16x16x32_bf16 v[54:57], v[156:159], v[200:203], v[54:57]
	v_mfma_f32_16x16x32_bf16 v[50:53], v[164:167], v[200:203], v[50:53]
	v_mfma_f32_16x16x32_bf16 v[46:49], v[156:159], v[208:211], v[46:49]
	v_mfma_f32_16x16x32_bf16 v[38:41], v[164:167], v[208:211], v[38:41]
	v_mfma_f32_16x16x32_bf16 v[30:33], v[156:159], v[216:219], v[30:33]
	v_mfma_f32_16x16x32_bf16 v[22:25], v[164:167], v[216:219], v[22:25]
	v_mfma_f32_16x16x32_bf16 v[42:45], v[168:171], v[184:187], v[42:45]
	v_mfma_f32_16x16x32_bf16 v[34:37], v[176:179], v[184:187], v[34:37]
	v_mfma_f32_16x16x32_bf16 v[26:29], v[168:171], v[196:199], v[26:29]
	v_mfma_f32_16x16x32_bf16 v[18:21], v[176:179], v[196:199], v[18:21]
	v_mfma_f32_16x16x32_bf16 v[14:17], v[168:171], v[204:207], v[14:17]
	v_mfma_f32_16x16x32_bf16 v[10:13], v[176:179], v[204:207], v[10:13]
	v_mfma_f32_16x16x32_bf16 v[6:9], v[168:171], v[212:215], v[6:9]
	v_mfma_f32_16x16x32_bf16 v[2:5], v[176:179], v[212:215], v[2:5]
	v_mfma_f32_16x16x32_bf16 v[42:45], v[172:175], v[188:191], v[42:45]
	v_mfma_f32_16x16x32_bf16 v[34:37], v[180:183], v[188:191], v[34:37]
	v_mfma_f32_16x16x32_bf16 v[26:29], v[172:175], v[200:203], v[26:29]
	v_mfma_f32_16x16x32_bf16 v[18:21], v[180:183], v[200:203], v[18:21]
	v_mfma_f32_16x16x32_bf16 v[14:17], v[172:175], v[208:211], v[14:17]
	v_mfma_f32_16x16x32_bf16 v[10:13], v[180:183], v[208:211], v[10:13]
	v_mfma_f32_16x16x32_bf16 v[6:9], v[172:175], v[216:219], v[6:9]
	v_mfma_f32_16x16x32_bf16 v[2:5], v[180:183], v[216:219], v[2:5]
	s_barrier
	s_add_i32 s50, 0, 0x18000
	s_add_i32 s51, 0, 0x1c000
	v_add_u32_e32 v164, s50, v150
	v_add_u32_e32 v180, s51, v150
	ds_read_b128 v[152:155], v164
	ds_read_b128 v[156:159], v164 offset:1024
	ds_read_b128 v[160:163], v164 offset:2048
	ds_read_b128 v[164:167], v164 offset:3072
	ds_read_b128 v[168:171], v180
	ds_read_b128 v[172:175], v180 offset:1024
	ds_read_b128 v[176:179], v180 offset:2048
	ds_read_b128 v[180:183], v180 offset:3072
	s_add_u32 s38, s38, 0x40000
	s_addc_u32 s39, s39, 0
	s_mov_b32 m0, s34
	v_lshl_add_u64 v[226:227], s[38:39], 0, v[134:135]
	ds_read_b128 v[184:187], v151 offset:32768
	ds_read_b128 v[188:191], v151 offset:33792
	ds_read_b128 v[196:199], v151 offset:34816
	ds_read_b128 v[200:203], v151 offset:35840
	ds_read_b128 v[204:207], v151 offset:36864
	ds_read_b128 v[208:211], v151 offset:37888
	ds_read_b128 v[212:215], v151 offset:38912
	ds_read_b128 v[216:219], v151 offset:39936
	global_load_lds_dwordx4 v[226:227], off
	v_lshl_add_u64 v[226:227], s[38:39], 0, v[136:137]
	s_mov_b32 m0, s35
	s_nop 0
	global_load_lds_dwordx4 v[226:227], off
	s_waitcnt vmcnt(8)
	s_waitcnt lgkmcnt(0)
	s_barrier
	s_waitcnt lgkmcnt(0)
	v_mfma_f32_16x16x32_bf16 v[126:129], v[152:155], v[184:187], v[126:129]
	v_mfma_f32_16x16x32_bf16 v[122:125], v[160:163], v[184:187], v[122:125]
	v_mfma_f32_16x16x32_bf16 v[118:121], v[152:155], v[196:199], v[118:121]
	v_mfma_f32_16x16x32_bf16 v[114:117], v[160:163], v[196:199], v[114:117]
	v_mfma_f32_16x16x32_bf16 v[110:113], v[152:155], v[204:207], v[110:113]
	v_mfma_f32_16x16x32_bf16 v[102:105], v[160:163], v[204:207], v[102:105]
	v_mfma_f32_16x16x32_bf16 v[94:97], v[152:155], v[212:215], v[94:97]
	v_mfma_f32_16x16x32_bf16 v[86:89], v[160:163], v[212:215], v[86:89]
	v_mfma_f32_16x16x32_bf16 v[126:129], v[156:159], v[188:191], v[126:129]
	v_mfma_f32_16x16x32_bf16 v[122:125], v[164:167], v[188:191], v[122:125]
	v_mfma_f32_16x16x32_bf16 v[118:121], v[156:159], v[200:203], v[118:121]
	v_mfma_f32_16x16x32_bf16 v[114:117], v[164:167], v[200:203], v[114:117]
	v_mfma_f32_16x16x32_bf16 v[110:113], v[156:159], v[208:211], v[110:113]
	v_mfma_f32_16x16x32_bf16 v[102:105], v[164:167], v[208:211], v[102:105]
	v_mfma_f32_16x16x32_bf16 v[94:97], v[156:159], v[216:219], v[94:97]
	v_mfma_f32_16x16x32_bf16 v[86:89], v[164:167], v[216:219], v[86:89]
	v_mfma_f32_16x16x32_bf16 v[106:109], v[168:171], v[184:187], v[106:109]
	v_mfma_f32_16x16x32_bf16 v[98:101], v[176:179], v[184:187], v[98:101]
	v_mfma_f32_16x16x32_bf16 v[90:93], v[168:171], v[196:199], v[90:93]
	v_mfma_f32_16x16x32_bf16 v[82:85], v[176:179], v[196:199], v[82:85]
	v_mfma_f32_16x16x32_bf16 v[78:81], v[168:171], v[204:207], v[78:81]
	v_mfma_f32_16x16x32_bf16 v[74:77], v[176:179], v[204:207], v[74:77]
	v_mfma_f32_16x16x32_bf16 v[70:73], v[168:171], v[212:215], v[70:73]
	v_mfma_f32_16x16x32_bf16 v[66:69], v[176:179], v[212:215], v[66:69]
	v_mfma_f32_16x16x32_bf16 v[106:109], v[172:175], v[188:191], v[106:109]
	v_mfma_f32_16x16x32_bf16 v[98:101], v[180:183], v[188:191], v[98:101]
	v_mfma_f32_16x16x32_bf16 v[90:93], v[172:175], v[200:203], v[90:93]
	v_mfma_f32_16x16x32_bf16 v[82:85], v[180:183], v[200:203], v[82:85]
	v_mfma_f32_16x16x32_bf16 v[78:81], v[172:175], v[208:211], v[78:81]
	v_mfma_f32_16x16x32_bf16 v[74:77], v[180:183], v[208:211], v[74:77]
	v_mfma_f32_16x16x32_bf16 v[70:73], v[172:175], v[216:219], v[70:73]
	v_mfma_f32_16x16x32_bf16 v[66:69], v[180:183], v[216:219], v[66:69]
	s_barrier
	s_add_i32 s38, s50, s15
	v_lshl_add_u64 v[192:193], v[192:193], 0, s[22:23]
	s_mov_b32 m0, s38
	ds_read_b128 v[184:187], v151 offset:49152
	ds_read_b128 v[188:191], v151 offset:50176
	ds_read_b128 v[196:199], v151 offset:51200
	ds_read_b128 v[200:203], v151 offset:52224
	ds_read_b128 v[204:207], v151 offset:53248
	ds_read_b128 v[208:211], v151 offset:54272
	ds_read_b128 v[212:215], v151 offset:55296
	ds_read_b128 v[216:219], v151 offset:56320
	global_load_lds_dwordx4 v[192:193], off
	s_add_i32 m0, s38, 0x2000
	s_add_u32 s36, s36, 0x40080
	v_lshl_add_u64 v[192:193], v[220:221], 0, s[22:23]
	s_addc_u32 s37, s37, 0
	s_add_i32 s38, s51, s15
	global_load_lds_dwordx4 v[192:193], off
	v_lshl_add_u64 v[192:193], s[36:37], 0, v[130:131]
	s_mov_b32 m0, s38
	s_nop 0
	global_load_lds_dwordx4 v[192:193], off
	v_lshl_add_u64 v[192:193], s[36:37], 0, v[132:133]
	s_add_i32 m0, s38, 0x2000
	s_nop 0
	global_load_lds_dwordx4 v[192:193], off
	v_lshl_add_u64 v[192:193], v[222:223], 0, s[22:23]
	s_mov_b32 m0, s41
	s_nop 0
	global_load_lds_dwordx4 v[192:193], off
	v_lshl_add_u64 v[192:193], v[224:225], 0, s[22:23]
	s_mov_b32 m0, s42
	s_nop 0
	global_load_lds_dwordx4 v[192:193], off
	s_waitcnt vmcnt(8)
	s_waitcnt lgkmcnt(0)
	s_barrier
	s_waitcnt lgkmcnt(0)
	v_mfma_f32_16x16x32_bf16 v[62:65], v[152:155], v[184:187], v[62:65]
	v_mfma_f32_16x16x32_bf16 v[58:61], v[160:163], v[184:187], v[58:61]
	v_mfma_f32_16x16x32_bf16 v[54:57], v[152:155], v[196:199], v[54:57]
	v_mfma_f32_16x16x32_bf16 v[50:53], v[160:163], v[196:199], v[50:53]
	v_mfma_f32_16x16x32_bf16 v[46:49], v[152:155], v[204:207], v[46:49]
	v_mfma_f32_16x16x32_bf16 v[38:41], v[160:163], v[204:207], v[38:41]
	v_mfma_f32_16x16x32_bf16 v[30:33], v[152:155], v[212:215], v[30:33]
	v_mfma_f32_16x16x32_bf16 v[22:25], v[160:163], v[212:215], v[22:25]
	v_mfma_f32_16x16x32_bf16 v[62:65], v[156:159], v[188:191], v[62:65]
	v_mfma_f32_16x16x32_bf16 v[58:61], v[164:167], v[188:191], v[58:61]
	v_mfma_f32_16x16x32_bf16 v[54:57], v[156:159], v[200:203], v[54:57]
	v_mfma_f32_16x16x32_bf16 v[50:53], v[164:167], v[200:203], v[50:53]
	v_mfma_f32_16x16x32_bf16 v[46:49], v[156:159], v[208:211], v[46:49]
	v_mfma_f32_16x16x32_bf16 v[38:41], v[164:167], v[208:211], v[38:41]
	v_mfma_f32_16x16x32_bf16 v[30:33], v[156:159], v[216:219], v[30:33]
	v_mfma_f32_16x16x32_bf16 v[22:25], v[164:167], v[216:219], v[22:25]
	v_mfma_f32_16x16x32_bf16 v[42:45], v[168:171], v[184:187], v[42:45]
	v_mfma_f32_16x16x32_bf16 v[34:37], v[176:179], v[184:187], v[34:37]
	v_mfma_f32_16x16x32_bf16 v[26:29], v[168:171], v[196:199], v[26:29]
	v_mfma_f32_16x16x32_bf16 v[18:21], v[176:179], v[196:199], v[18:21]
	v_mfma_f32_16x16x32_bf16 v[14:17], v[168:171], v[204:207], v[14:17]
	v_mfma_f32_16x16x32_bf16 v[10:13], v[176:179], v[204:207], v[10:13]
	v_mfma_f32_16x16x32_bf16 v[6:9], v[168:171], v[212:215], v[6:9]
	v_mfma_f32_16x16x32_bf16 v[2:5], v[176:179], v[212:215], v[2:5]
	v_mfma_f32_16x16x32_bf16 v[42:45], v[172:175], v[188:191], v[42:45]
	v_mfma_f32_16x16x32_bf16 v[34:37], v[180:183], v[188:191], v[34:37]
	v_mfma_f32_16x16x32_bf16 v[26:29], v[172:175], v[200:203], v[26:29]
	v_mfma_f32_16x16x32_bf16 v[18:21], v[180:183], v[200:203], v[18:21]
	v_mfma_f32_16x16x32_bf16 v[14:17], v[172:175], v[208:211], v[14:17]
	v_mfma_f32_16x16x32_bf16 v[10:13], v[180:183], v[208:211], v[10:13]
	v_mfma_f32_16x16x32_bf16 v[6:9], v[172:175], v[216:219], v[6:9]
	v_mfma_f32_16x16x32_bf16 v[2:5], v[180:183], v[216:219], v[2:5]
	s_barrier
	s_add_i32 s49, s49, 2
	s_add_u32 s30, s30, 0x100
	s_addc_u32 s31, s31, 0
	s_cmp_gt_u32 s49, 13
	s_cbranch_scc0 .LBB0_395
	s_setprio 0
	s_add_u32 s30, s25, 0xffffff00
	s_addc_u32 s31, s48, -1
	s_andn2_b64 vcc, exec, s[6:7]
	s_cbranch_vccnz .LBB0_386
	v_mov_b32_e32 v2, 0
	s_mov_b32 s8, s45
	s_mov_b32 s0, s24
	s_mov_b64 s[10:11], s[28:29]
	s_mov_b32 s40, s47
	v_mov_b32_e32 v3, 0
	v_mov_b64_e32 v[4:5], 0
	v_mov_b64_e32 v[6:7], 0
	v_mov_b64_e32 v[8:9], 0
	v_mov_b64_e32 v[10:11], 0
	v_mov_b64_e32 v[12:13], 0
	v_mov_b64_e32 v[14:15], 0
	v_mov_b64_e32 v[16:17], 0
	v_mov_b64_e32 v[18:19], 0
	v_mov_b64_e32 v[20:21], 0
	v_mov_b64_e32 v[22:23], 0
	v_mov_b64_e32 v[24:25], 0
	v_mov_b64_e32 v[26:27], 0
	v_mov_b64_e32 v[28:29], 0
	v_mov_b64_e32 v[30:31], 0
	v_mov_b64_e32 v[32:33], 0
	v_mov_b64_e32 v[34:35], 0
	v_mov_b64_e32 v[36:37], 0
	v_mov_b64_e32 v[38:39], 0
	v_mov_b64_e32 v[40:41], 0
	v_mov_b64_e32 v[42:43], 0
	v_mov_b64_e32 v[44:45], 0
	v_mov_b64_e32 v[46:47], 0
	v_mov_b64_e32 v[48:49], 0
	v_mov_b64_e32 v[50:51], 0
	v_mov_b64_e32 v[52:53], 0
	v_mov_b64_e32 v[54:55], 0
	v_mov_b64_e32 v[56:57], 0
	v_mov_b64_e32 v[58:59], 0
	v_mov_b64_e32 v[60:61], 0
	v_mov_b64_e32 v[62:63], 0
	v_mov_b64_e32 v[64:65], 0
	v_mov_b64_e32 v[66:67], 0
	v_mov_b64_e32 v[68:69], 0
	v_mov_b64_e32 v[70:71], 0
	v_mov_b64_e32 v[72:73], 0
	v_mov_b64_e32 v[74:75], 0
	v_mov_b64_e32 v[76:77], 0
	v_mov_b64_e32 v[78:79], 0
	v_mov_b64_e32 v[80:81], 0
	v_mov_b64_e32 v[82:83], 0
	v_mov_b64_e32 v[84:85], 0
	v_mov_b64_e32 v[86:87], 0
	v_mov_b64_e32 v[88:89], 0
	v_mov_b64_e32 v[90:91], 0
	v_mov_b64_e32 v[92:93], 0
	v_mov_b64_e32 v[94:95], 0
	v_mov_b64_e32 v[96:97], 0
	v_mov_b64_e32 v[98:99], 0
	v_mov_b64_e32 v[100:101], 0
	v_mov_b64_e32 v[102:103], 0
	v_mov_b64_e32 v[104:105], 0
	v_mov_b64_e32 v[106:107], 0
	v_mov_b64_e32 v[108:109], 0
	v_mov_b64_e32 v[110:111], 0
	v_mov_b64_e32 v[112:113], 0
	v_mov_b64_e32 v[114:115], 0
	v_mov_b64_e32 v[116:117], 0
	v_mov_b64_e32 v[118:119], 0
	v_mov_b64_e32 v[120:121], 0
	v_mov_b64_e32 v[122:123], 0
	v_mov_b64_e32 v[124:125], 0
	v_mov_b64_e32 v[126:127], 0
	v_mov_b64_e32 v[128:129], 0
	s_andn2_b64 vcc, exec, s[4:5]
	s_cbranch_vccnz .LBB0_387

.LBB0_580:
	s_add_i32 m0, s51, 0x18000
	v_lshl_add_u64 v[10:11], v[10:11], 0, s[52:53]
	s_waitcnt vmcnt(2)
	s_barrier
	global_load_lds_dwordx4 v[10:11], off
	v_lshl_add_u64 v[10:11], v[12:13], 0, s[52:53]
	s_add_i32 m0, s51, 0x1a000
	s_add_i32 s23, s51, 0x8000
	global_load_lds_dwordx4 v[10:11], off
	v_lshl_add_u64 v[10:11], v[18:19], 0, s[52:53]
	s_mov_b32 m0, s23
	s_add_i32 s28, s51, 0xa000
	global_load_lds_dwordx4 v[10:11], off
	v_lshl_add_u64 v[10:11], v[20:21], 0, s[52:53]
	s_mov_b32 m0, s28
	v_and_b32_e32 v157, 15, v26
	global_load_lds_dwordx4 v[10:11], off
	s_add_i32 m0, s51, 0x1c000
	v_lshl_add_u64 v[10:11], v[14:15], 0, s[52:53]
	global_load_lds_dwordx4 v[10:11], off
	v_lshl_add_u64 v[10:11], v[16:17], 0, s[52:53]
	s_add_i32 m0, s51, 0x1e000
	v_bfe_u32 v27, v26, 4, 2
	global_load_lds_dwordx4 v[10:11], off
	v_lshlrev_b32_e32 v28, 6, v157
	v_lshlrev_b32_e32 v26, 2, v26
	s_and_b32 s5, s5, 3
	s_lshl_b32 s35, s4, 6
	v_lshl_or_b32 v29, v27, 4, v28
	s_lshl_b32 s4, s4, 13
	v_and_b32_e32 v26, 32, v26
	v_and_b32_e32 v10, 1, v24
	v_lshlrev_b32_e32 v11, 1, v25
	v_lshlrev_b32_e32 v178, 3, v27
	v_bitop3_b32 v30, v29, s4, v26 bitop3:0xde
	s_lshl_b32 s22, s5, 5
	s_lshl_b32 s4, s5, 12
	s_waitcnt vmcnt(6)
	v_lshl_add_u32 v183, v10, 6, v11
	v_and_b32_e32 v10, 1, v22
	v_lshlrev_b32_e32 v11, 1, v23
	v_bitop3_b32 v179, v29, s4, v26 bitop3:0xde
	s_cmpk_lt_u32 s12, 0x100
	v_or_b32_e32 v181, s22, v178
	v_mov_b32_e32 v29, v2
	v_lshl_add_u32 v184, v10, 6, v11
	v_mov_b32_e32 v10, 0
	v_or_b32_e32 v177, s35, v157
	s_cselect_b64 s[78:79], -1, 0
	s_lshl_b32 s29, s5, 7
	v_lshlrev_b32_e32 v180, 5, v27
	s_and_b32 s21, s12, 0xffffff00
	v_or_b32_e32 v182, 0x80, v181
	s_add_i32 s56, s35, 0x80
	v_lshl_add_u64 v[158:159], s[58:59], 0, v[28:29]
	s_mov_b32 s42, 0
	v_add_u32_e32 v185, 0, v30
	v_readlane_b32 s57, v255, 24
	v_readlane_b32 s14, v255, 33
	v_mov_b32_e32 v11, 0
	v_mov_b64_e32 v[12:13], 0
	v_mov_b64_e32 v[14:15], 0
	v_mov_b64_e32 v[16:17], 0
	v_mov_b64_e32 v[18:19], 0
	v_mov_b64_e32 v[20:21], 0
	v_mov_b64_e32 v[22:23], 0
	v_mov_b64_e32 v[24:25], 0
	v_mov_b64_e32 v[26:27], 0
	v_mov_b64_e32 v[28:29], 0
	v_mov_b64_e32 v[30:31], 0
	v_mov_b64_e32 v[32:33], 0
	v_mov_b64_e32 v[34:35], 0
	v_mov_b64_e32 v[36:37], 0
	v_mov_b64_e32 v[38:39], 0
	v_mov_b64_e32 v[40:41], 0
	v_mov_b64_e32 v[42:43], 0
	v_mov_b64_e32 v[44:45], 0
	v_mov_b64_e32 v[46:47], 0
	v_mov_b64_e32 v[48:49], 0
	v_mov_b64_e32 v[50:51], 0
	v_mov_b64_e32 v[52:53], 0
	v_mov_b64_e32 v[54:55], 0
	v_mov_b64_e32 v[56:57], 0
	v_mov_b64_e32 v[58:59], 0
	v_mov_b64_e32 v[60:61], 0
	v_mov_b64_e32 v[62:63], 0
	v_mov_b64_e32 v[64:65], 0
	v_mov_b64_e32 v[66:67], 0
	v_mov_b64_e32 v[68:69], 0
	v_mov_b64_e32 v[70:71], 0
	v_mov_b64_e32 v[72:73], 0
	v_mov_b64_e32 v[74:75], 0
	v_mov_b64_e32 v[76:77], 0
	v_mov_b64_e32 v[78:79], 0
	v_mov_b64_e32 v[80:81], 0
	v_mov_b64_e32 v[82:83], 0
	v_mov_b64_e32 v[84:85], 0
	v_mov_b64_e32 v[86:87], 0
	v_mov_b64_e32 v[88:89], 0
	v_mov_b64_e32 v[90:91], 0
	v_mov_b64_e32 v[92:93], 0
	v_mov_b64_e32 v[94:95], 0
	v_mov_b64_e32 v[96:97], 0
	v_mov_b64_e32 v[98:99], 0
	v_mov_b64_e32 v[100:101], 0
	v_mov_b64_e32 v[102:103], 0
	v_mov_b64_e32 v[104:105], 0
	v_mov_b64_e32 v[106:107], 0
	v_mov_b64_e32 v[108:109], 0
	v_mov_b64_e32 v[110:111], 0
	v_mov_b64_e32 v[112:113], 0
	v_mov_b64_e32 v[114:115], 0
	v_mov_b64_e32 v[116:117], 0
	v_mov_b64_e32 v[118:119], 0
	v_mov_b64_e32 v[120:121], 0
	v_mov_b64_e32 v[122:123], 0
	v_mov_b64_e32 v[124:125], 0
	v_mov_b64_e32 v[126:127], 0
	v_mov_b64_e32 v[128:129], 0
	v_mov_b64_e32 v[130:131], 0
	v_mov_b64_e32 v[132:133], 0
	v_mov_b64_e32 v[134:135], 0
	v_mov_b64_e32 v[136:137], 0
	s_mov_b64 s[84:85], s[8:9]
	s_barrier
	s_branch .LBB0_582
.LBB0_581:
	v_mov_b32_e32 v10, 0
	s_mov_b32 s57, s82
	s_mov_b32 s14, s15
	s_mov_b32 s65, s13
	v_mov_b32_e32 v11, 0
	s_mov_b64 s[36:37], s[76:77]
	s_mov_b64 s[80:81], s[90:91]
	s_mov_b32 s72, s86
	s_mov_b32 s70, s26
	s_mov_b64 s[68:69], s[88:89]
	s_mov_b32 s42, s12
	s_andn2_b64 vcc, exec, s[4:5]
	s_mov_b64 s[8:9], s[84:85]
	s_cbranch_vccz .LBB0_701

.LBB0_601:
	s_cmp_lg_u32 s65, 0
	s_cselect_b64 s[38:39], -1, 0
	s_and_b64 vcc, exec, s[38:39]
	s_cbranch_vccz .LBB0_652
	s_lshl_b32 s8, s57, 8
	s_and_b32 s8, s8, 0x300
	s_lshl_b32 s41, s14, 8
	s_waitcnt lgkmcnt(0)
	v_pk_mul_f32 v[160:161], v[134:135], v[146:147]
	v_mov_b64_e32 v[134:135], 0
	v_pk_mul_f32 v[162:163], v[136:137], v[148:149]
	v_mov_b64_e32 v[136:137], 0
	s_add_i32 s8, s8, s35
	s_lshl_b32 s9, s57, 2
	v_or_b32_e32 v166, s41, v181
	v_cvt_pk_bf16_f32 v160, v160, v161
	v_cvt_pk_bf16_f32 v161, v162, v163
	v_pk_mul_f32 v[162:163], v[130:131], v[150:151]
	v_mov_b64_e32 v[130:131], 0
	v_pk_mul_f32 v[164:165], v[132:133], v[152:153]
	v_mov_b64_e32 v[132:133], 0
	s_ashr_i32 s8, s8, 6
	s_and_b32 s9, s9, -16
	v_cvt_pk_bf16_f32 v162, v162, v163
	v_cvt_pk_bf16_f32 v163, v164, v165
	v_ashrrev_i32_e32 v164, 31, v166
	s_add_i32 s8, s9, s8
	v_lshrrev_b32_e32 v164, 27, v164
	s_addk_i32 s8, 0xff90
	v_add_u32_e32 v167, v166, v164
	s_ashr_i32 s9, s8, 31
	v_ashrrev_i32_e32 v164, 5, v167
	s_lshl_b64 s[8:9], s[8:9], 8
	v_ashrrev_i32_e32 v165, 31, v164
	v_lshl_add_u64 v[164:165], s[8:9], 0, v[164:165]
	v_and_b32_e32 v167, 0xffffffe0, v167
	v_lshlrev_b64 v[164:165], 12, v[164:165]
	v_sub_u32_e32 v166, v166, v167
	v_lshl_add_u64 v[164:165], v[158:159], 0, v[164:165]
	v_ashrrev_i32_e32 v167, 31, v166
	v_lshl_add_u64 v[164:165], v[166:167], 1, v[164:165]
	s_cselect_b32 s99, 1, 0
	s_cmp_lg_u32 s4, 0
	s_cbranch_scc0 .Lwt_g3_p0
	global_store_dwordx4 v[164:165], v[160:163], off sc1
	s_branch .Lwt_g3_d0

.Lwt_g3_d0:
	s_cmp_lg_u32 s99, 0
	v_or_b32_e32 v166, s41, v182
	v_pk_mul_f32 v[164:165], v[100:101], v[144:145]
	v_mov_b64_e32 v[100:101], 0
	v_pk_mul_f32 v[160:161], v[102:103], v[138:139]
	v_mov_b64_e32 v[102:103], 0
	v_pk_mul_f32 v[162:163], v[104:105], v[140:141]
	v_mov_b64_e32 v[104:105], 0
	v_cvt_pk_bf16_f32 v160, v160, v161
	v_cvt_pk_bf16_f32 v161, v162, v163
	v_pk_mul_f32 v[162:163], v[98:99], v[142:143]
	v_mov_b64_e32 v[98:99], 0
	s_nop 0
	v_cvt_pk_bf16_f32 v162, v162, v163
	v_cvt_pk_bf16_f32 v163, v164, v165
	v_ashrrev_i32_e32 v164, 31, v166
	v_lshrrev_b32_e32 v164, 27, v164
	v_add_u32_e32 v167, v166, v164
	v_ashrrev_i32_e32 v164, 5, v167
	v_ashrrev_i32_e32 v165, 31, v164
	v_lshl_add_u64 v[164:165], s[8:9], 0, v[164:165]
	v_and_b32_e32 v167, 0xffffffe0, v167
	v_lshlrev_b64 v[164:165], 12, v[164:165]
	v_sub_u32_e32 v166, v166, v167
	v_lshl_add_u64 v[164:165], v[158:159], 0, v[164:165]
	v_ashrrev_i32_e32 v167, 31, v166
	v_lshl_add_u64 v[164:165], v[166:167], 1, v[164:165]
	s_cselect_b32 s99, 1, 0
	s_cmp_lg_u32 s4, 0
	s_cbranch_scc0 .Lwt_g3_p1
	global_store_dwordx4 v[164:165], v[160:163], off sc1
	s_branch .Lwt_g3_d1

.LBB0_607:
	s_waitcnt lgkmcnt(0)
	v_pk_mul_f32 v[188:189], v[136:137], v[146:147] op_sel_hi:[1,0]
	v_mov_b64_e32 v[136:137], 0
	v_pk_mul_f32 v[186:187], v[134:135], v[146:147] op_sel_hi:[1,0]
	v_mov_b64_e32 v[134:135], 0
	v_pk_mul_f32 v[190:191], v[132:133], v[146:147] op_sel_hi:[1,0]
	v_mov_b64_e32 v[132:133], 0
	v_pk_mul_f32 v[192:193], v[130:131], v[146:147] op_sel_hi:[1,0]
	v_mov_b64_e32 v[130:131], 0
	v_cvt_pk_bf16_f32 v186, v186, v187
	v_cvt_pk_bf16_f32 v187, v188, v189
	v_cvt_pk_bf16_f32 v188, v192, v193
	v_cvt_pk_bf16_f32 v189, v190, v191
	s_andn2_b64 vcc, exec, s[8:9]
	s_mov_b64 s[8:9], -1
	s_cselect_b32 s99, 1, 0
	s_cmp_lg_u32 s4, 0
	s_cbranch_scc0 .Lwt_g3_p2
	global_store_dwordx4 v[168:169], v[186:189], off sc1
	s_branch .Lwt_g3_d2

.LBB0_611:
	v_mov_b32_e32 v160, v146
	v_mov_b32_e32 v161, v146
	v_mov_b32_e32 v162, v146
	v_mov_b32_e32 v163, v146
	v_pk_mul_f32 v[164:165], v[104:105], v[162:163]
	v_mov_b64_e32 v[104:105], 0
	v_pk_mul_f32 v[166:167], v[102:103], v[160:161]
	v_mov_b64_e32 v[102:103], 0
	v_pk_mul_f32 v[186:187], v[100:101], v[162:163]
	v_mov_b64_e32 v[100:101], 0
	v_pk_mul_f32 v[162:163], v[98:99], v[160:161]
	v_mov_b64_e32 v[98:99], 0
	v_cvt_pk_bf16_f32 v160, v166, v167
	v_cvt_pk_bf16_f32 v161, v164, v165
	v_cvt_pk_bf16_f32 v162, v162, v163
	v_cvt_pk_bf16_f32 v163, v186, v187
	s_cselect_b32 s99, 1, 0
	s_cmp_lg_u32 s4, 0
	s_cbranch_scc0 .Lwt_g3_p3
	global_store_dwordx4 v[168:169], v[160:163], off sc1
	s_branch .Lwt_g3_d3

.LBB0_614:
	s_lshl_b32 s38, s57, 8
	s_and_b32 s38, s38, 0x300
	s_lshl_b32 s41, s14, 8
	s_waitcnt lgkmcnt(0)
	v_pk_mul_f32 v[160:161], v[118:119], v[146:147]
	v_mov_b64_e32 v[118:119], 0
	v_pk_mul_f32 v[162:163], v[120:121], v[148:149]
	v_mov_b64_e32 v[120:121], 0
	s_add_i32 s38, s38, s35
	s_lshl_b32 s39, s57, 2
	v_or_b32_e32 v166, s41, v181
	v_cvt_pk_bf16_f32 v160, v160, v161
	v_cvt_pk_bf16_f32 v161, v162, v163
	v_pk_mul_f32 v[162:163], v[114:115], v[150:151]
	v_mov_b64_e32 v[114:115], 0
	v_pk_mul_f32 v[164:165], v[116:117], v[152:153]
	v_mov_b64_e32 v[116:117], 0
	s_ashr_i32 s38, s38, 6
	s_and_b32 s39, s39, -16
	v_cvt_pk_bf16_f32 v162, v162, v163
	v_cvt_pk_bf16_f32 v163, v164, v165
	v_ashrrev_i32_e32 v164, 31, v166
	s_add_i32 s38, s39, s38
	v_lshrrev_b32_e32 v164, 27, v164
	s_addk_i32 s38, 0xff90
	v_add_u32_e32 v167, v166, v164
	s_ashr_i32 s39, s38, 31
	v_ashrrev_i32_e32 v164, 5, v167
	s_lshl_b64 s[38:39], s[38:39], 8
	v_ashrrev_i32_e32 v165, 31, v164
	v_lshl_add_u64 v[164:165], s[38:39], 0, v[164:165]
	v_and_b32_e32 v167, 0xffffffe0, v167
	v_lshlrev_b64 v[164:165], 12, v[164:165]
	v_sub_u32_e32 v166, v166, v167
	v_lshl_add_u64 v[164:165], v[158:159], 0, v[164:165]
	v_ashrrev_i32_e32 v167, 31, v166
	v_lshl_add_u64 v[164:165], v[166:167], 1, v[164:165]
	s_cselect_b32 s99, 1, 0
	s_cmp_lg_u32 s4, 0
	s_cbranch_scc0 .Lwt_g3_p4
	global_store_dwordx4 v[164:165], v[160:163], off offset:2048 sc1
	s_branch .Lwt_g3_d4

.Lwt_g3_d4:
	s_cmp_lg_u32 s99, 0
	v_or_b32_e32 v166, s41, v182
	v_pk_mul_f32 v[164:165], v[84:85], v[144:145]
	v_mov_b64_e32 v[84:85], 0
	v_pk_mul_f32 v[160:161], v[86:87], v[138:139]
	v_mov_b64_e32 v[86:87], 0
	v_pk_mul_f32 v[162:163], v[88:89], v[140:141]
	v_mov_b64_e32 v[88:89], 0
	v_cvt_pk_bf16_f32 v160, v160, v161
	v_cvt_pk_bf16_f32 v161, v162, v163
	v_pk_mul_f32 v[162:163], v[82:83], v[142:143]
	v_mov_b64_e32 v[82:83], 0
	s_nop 0
	v_cvt_pk_bf16_f32 v162, v162, v163
	v_cvt_pk_bf16_f32 v163, v164, v165
	v_ashrrev_i32_e32 v164, 31, v166
	v_lshrrev_b32_e32 v164, 27, v164
	v_add_u32_e32 v167, v166, v164
	v_ashrrev_i32_e32 v164, 5, v167
	v_ashrrev_i32_e32 v165, 31, v164
	v_lshl_add_u64 v[164:165], s[38:39], 0, v[164:165]
	v_and_b32_e32 v167, 0xffffffe0, v167
	v_lshlrev_b64 v[164:165], 12, v[164:165]
	v_sub_u32_e32 v166, v166, v167
	v_lshl_add_u64 v[164:165], v[158:159], 0, v[164:165]
	v_ashrrev_i32_e32 v167, 31, v166
	v_lshl_add_u64 v[164:165], v[166:167], 1, v[164:165]
	s_cselect_b32 s99, 1, 0
	s_cmp_lg_u32 s4, 0
	s_cbranch_scc0 .Lwt_g3_p5
	global_store_dwordx4 v[164:165], v[160:163], off offset:2048 sc1
	s_branch .Lwt_g3_d5

.LBB0_619:
	s_waitcnt lgkmcnt(0)
	v_pk_mul_f32 v[188:189], v[120:121], v[148:149] op_sel_hi:[1,0]
	v_mov_b64_e32 v[120:121], 0
	v_pk_mul_f32 v[186:187], v[118:119], v[148:149] op_sel_hi:[1,0]
	v_mov_b64_e32 v[118:119], 0
	v_pk_mul_f32 v[190:191], v[116:117], v[148:149] op_sel_hi:[1,0]
	v_mov_b64_e32 v[116:117], 0
	v_pk_mul_f32 v[192:193], v[114:115], v[148:149] op_sel_hi:[1,0]
	v_mov_b64_e32 v[114:115], 0
	v_cvt_pk_bf16_f32 v186, v186, v187
	v_cvt_pk_bf16_f32 v187, v188, v189
	v_cvt_pk_bf16_f32 v188, v192, v193
	v_cvt_pk_bf16_f32 v189, v190, v191
	s_andn2_b64 vcc, exec, s[38:39]
	s_mov_b64 s[38:39], -1
	s_cselect_b32 s99, 1, 0
	s_cmp_lg_u32 s4, 0
	s_cbranch_scc0 .Lwt_g3_p6
	global_store_dwordx4 v[168:169], v[186:189], off sc1
	s_branch .Lwt_g3_d6

.LBB0_623:
	v_mov_b32_e32 v160, v148
	v_mov_b32_e32 v161, v148
	v_mov_b32_e32 v162, v148
	v_mov_b32_e32 v163, v148
	v_pk_mul_f32 v[164:165], v[88:89], v[162:163]
	v_mov_b64_e32 v[88:89], 0
	v_pk_mul_f32 v[166:167], v[86:87], v[160:161]
	v_mov_b64_e32 v[86:87], 0
	v_pk_mul_f32 v[186:187], v[84:85], v[162:163]
	v_mov_b64_e32 v[84:85], 0
	v_pk_mul_f32 v[162:163], v[82:83], v[160:161]
	v_mov_b64_e32 v[82:83], 0
	v_cvt_pk_bf16_f32 v160, v166, v167
	v_cvt_pk_bf16_f32 v161, v164, v165
	v_cvt_pk_bf16_f32 v162, v162, v163
	v_cvt_pk_bf16_f32 v163, v186, v187
	s_cselect_b32 s99, 1, 0
	s_cmp_lg_u32 s4, 0
	s_cbranch_scc0 .Lwt_g3_p7
	global_store_dwordx4 v[168:169], v[160:163], off sc1
	s_branch .Lwt_g3_d7

.LBB0_626:
	s_lshl_b32 s38, s57, 8
	s_and_b32 s38, s38, 0x300
	s_lshl_b32 s41, s14, 8
	s_waitcnt lgkmcnt(0)
	v_pk_mul_f32 v[160:161], v[70:71], v[146:147]
	v_mov_b64_e32 v[70:71], 0
	v_pk_mul_f32 v[162:163], v[72:73], v[148:149]
	v_mov_b64_e32 v[72:73], 0
	s_add_i32 s38, s38, s56
	s_lshl_b32 s39, s57, 2
	v_or_b32_e32 v166, s41, v181
	v_cvt_pk_bf16_f32 v160, v160, v161
	v_cvt_pk_bf16_f32 v161, v162, v163
	v_pk_mul_f32 v[162:163], v[66:67], v[150:151]
	v_mov_b64_e32 v[66:67], 0
	v_pk_mul_f32 v[164:165], v[68:69], v[152:153]
	v_mov_b64_e32 v[68:69], 0
	s_ashr_i32 s38, s38, 6
	s_and_b32 s39, s39, -16
	v_cvt_pk_bf16_f32 v162, v162, v163
	v_cvt_pk_bf16_f32 v163, v164, v165
	v_ashrrev_i32_e32 v164, 31, v166
	s_add_i32 s38, s39, s38
	v_lshrrev_b32_e32 v164, 27, v164
	s_addk_i32 s38, 0xff90
	v_add_u32_e32 v167, v166, v164
	s_ashr_i32 s39, s38, 31
	v_ashrrev_i32_e32 v164, 5, v167
	s_lshl_b64 s[38:39], s[38:39], 8
	v_ashrrev_i32_e32 v165, 31, v164
	v_lshl_add_u64 v[164:165], s[38:39], 0, v[164:165]
	v_and_b32_e32 v167, 0xffffffe0, v167
	v_lshlrev_b64 v[164:165], 12, v[164:165]
	v_sub_u32_e32 v166, v166, v167
	v_lshl_add_u64 v[164:165], v[158:159], 0, v[164:165]
	v_ashrrev_i32_e32 v167, 31, v166
	v_lshl_add_u64 v[164:165], v[166:167], 1, v[164:165]
	s_cselect_b32 s99, 1, 0
	s_cmp_lg_u32 s4, 0
	s_cbranch_scc0 .Lwt_g3_p8
	global_store_dwordx4 v[164:165], v[160:163], off sc1
	s_branch .Lwt_g3_d8

.Lwt_g3_d8:
	s_cmp_lg_u32 s99, 0
	v_or_b32_e32 v166, s41, v182
	v_pk_mul_f32 v[164:165], v[36:37], v[144:145]
	v_mov_b64_e32 v[36:37], 0
	v_pk_mul_f32 v[160:161], v[38:39], v[138:139]
	v_mov_b64_e32 v[38:39], 0
	v_pk_mul_f32 v[162:163], v[40:41], v[140:141]
	v_mov_b64_e32 v[40:41], 0
	v_cvt_pk_bf16_f32 v160, v160, v161
	v_cvt_pk_bf16_f32 v161, v162, v163
	v_pk_mul_f32 v[162:163], v[34:35], v[142:143]
	v_mov_b64_e32 v[34:35], 0
	s_nop 0
	v_cvt_pk_bf16_f32 v162, v162, v163
	v_cvt_pk_bf16_f32 v163, v164, v165
	v_ashrrev_i32_e32 v164, 31, v166
	v_lshrrev_b32_e32 v164, 27, v164
	v_add_u32_e32 v167, v166, v164
	v_ashrrev_i32_e32 v164, 5, v167
	v_ashrrev_i32_e32 v165, 31, v164
	v_lshl_add_u64 v[164:165], s[38:39], 0, v[164:165]
	v_and_b32_e32 v167, 0xffffffe0, v167
	v_lshlrev_b64 v[164:165], 12, v[164:165]
	v_sub_u32_e32 v166, v166, v167
	v_lshl_add_u64 v[164:165], v[158:159], 0, v[164:165]
	v_ashrrev_i32_e32 v167, 31, v166
	v_lshl_add_u64 v[164:165], v[166:167], 1, v[164:165]
	s_cselect_b32 s99, 1, 0
	s_cmp_lg_u32 s4, 0
	s_cbranch_scc0 .Lwt_g3_p9
	global_store_dwordx4 v[164:165], v[160:163], off sc1
	s_branch .Lwt_g3_d9

.LBB0_631:
	s_waitcnt lgkmcnt(0)
	v_pk_mul_f32 v[188:189], v[72:73], v[138:139] op_sel_hi:[1,0]
	v_mov_b64_e32 v[72:73], 0
	v_pk_mul_f32 v[186:187], v[70:71], v[138:139] op_sel_hi:[1,0]
	v_mov_b64_e32 v[70:71], 0
	v_pk_mul_f32 v[190:191], v[68:69], v[138:139] op_sel_hi:[1,0]
	v_mov_b64_e32 v[68:69], 0
	v_pk_mul_f32 v[192:193], v[66:67], v[138:139] op_sel_hi:[1,0]
	v_mov_b64_e32 v[66:67], 0
	v_cvt_pk_bf16_f32 v186, v186, v187
	v_cvt_pk_bf16_f32 v187, v188, v189
	v_cvt_pk_bf16_f32 v188, v192, v193
	v_cvt_pk_bf16_f32 v189, v190, v191
	s_andn2_b64 vcc, exec, s[38:39]
	s_mov_b64 s[38:39], -1
	s_cselect_b32 s99, 1, 0
	s_cmp_lg_u32 s4, 0
	s_cbranch_scc0 .Lwt_g3_p10
	global_store_dwordx4 v[168:169], v[186:189], off sc1
	s_branch .Lwt_g3_d10

.LBB0_635:
	v_mov_b32_e32 v160, v138
	v_mov_b32_e32 v161, v138
	v_mov_b32_e32 v162, v138
	v_mov_b32_e32 v163, v138
	v_pk_mul_f32 v[164:165], v[40:41], v[162:163]
	v_mov_b64_e32 v[40:41], 0
	v_pk_mul_f32 v[166:167], v[38:39], v[160:161]
	v_mov_b64_e32 v[38:39], 0
	v_pk_mul_f32 v[186:187], v[36:37], v[162:163]
	v_mov_b64_e32 v[36:37], 0
	v_pk_mul_f32 v[162:163], v[34:35], v[160:161]
	v_mov_b64_e32 v[34:35], 0
	v_cvt_pk_bf16_f32 v160, v166, v167
	v_cvt_pk_bf16_f32 v161, v164, v165
	v_cvt_pk_bf16_f32 v162, v162, v163
	v_cvt_pk_bf16_f32 v163, v186, v187
	s_cselect_b32 s99, 1, 0
	s_cmp_lg_u32 s4, 0
	s_cbranch_scc0 .Lwt_g3_p11
	global_store_dwordx4 v[168:169], v[160:163], off sc1
	s_branch .Lwt_g3_d11

.LBB0_638:
	s_lshl_b32 s38, s57, 8
	s_and_b32 s38, s38, 0x300
	s_lshl_b32 s41, s14, 8
	s_waitcnt lgkmcnt(0)
	v_pk_mul_f32 v[160:161], v[54:55], v[146:147]
	v_mov_b64_e32 v[54:55], 0
	v_pk_mul_f32 v[162:163], v[56:57], v[148:149]
	v_mov_b64_e32 v[56:57], 0
	s_add_i32 s38, s38, s56
	s_lshl_b32 s39, s57, 2
	v_or_b32_e32 v166, s41, v181
	v_cvt_pk_bf16_f32 v160, v160, v161
	v_cvt_pk_bf16_f32 v161, v162, v163
	v_pk_mul_f32 v[162:163], v[50:51], v[150:151]
	v_mov_b64_e32 v[50:51], 0
	v_pk_mul_f32 v[164:165], v[52:53], v[152:153]
	v_mov_b64_e32 v[52:53], 0
	s_ashr_i32 s38, s38, 6
	s_and_b32 s39, s39, -16
	v_cvt_pk_bf16_f32 v162, v162, v163
	v_cvt_pk_bf16_f32 v163, v164, v165
	v_ashrrev_i32_e32 v164, 31, v166
	s_add_i32 s38, s39, s38
	v_lshrrev_b32_e32 v164, 27, v164
	s_addk_i32 s38, 0xff90
	v_add_u32_e32 v167, v166, v164
	s_ashr_i32 s39, s38, 31
	v_ashrrev_i32_e32 v164, 5, v167
	s_lshl_b64 s[38:39], s[38:39], 8
	v_ashrrev_i32_e32 v165, 31, v164
	v_lshl_add_u64 v[164:165], s[38:39], 0, v[164:165]
	v_and_b32_e32 v167, 0xffffffe0, v167
	v_lshlrev_b64 v[164:165], 12, v[164:165]
	v_sub_u32_e32 v166, v166, v167
	v_lshl_add_u64 v[164:165], v[158:159], 0, v[164:165]
	v_ashrrev_i32_e32 v167, 31, v166
	v_lshl_add_u64 v[164:165], v[166:167], 1, v[164:165]
	s_cselect_b32 s99, 1, 0
	s_cmp_lg_u32 s4, 0
	s_cbranch_scc0 .Lwt_g3_p12
	global_store_dwordx4 v[164:165], v[160:163], off offset:2048 sc1
	s_branch .Lwt_g3_d12

.Lwt_g3_d12:
	s_cmp_lg_u32 s99, 0
	v_or_b32_e32 v166, s41, v182
	v_pk_mul_f32 v[164:165], v[20:21], v[144:145]
	v_mov_b64_e32 v[20:21], 0
	v_pk_mul_f32 v[160:161], v[22:23], v[138:139]
	v_mov_b64_e32 v[22:23], 0
	v_pk_mul_f32 v[162:163], v[24:25], v[140:141]
	v_mov_b64_e32 v[24:25], 0
	v_cvt_pk_bf16_f32 v160, v160, v161
	v_cvt_pk_bf16_f32 v161, v162, v163
	v_pk_mul_f32 v[162:163], v[18:19], v[142:143]
	v_mov_b64_e32 v[18:19], 0
	s_nop 0
	v_cvt_pk_bf16_f32 v162, v162, v163
	v_cvt_pk_bf16_f32 v163, v164, v165
	v_ashrrev_i32_e32 v164, 31, v166
	v_lshrrev_b32_e32 v164, 27, v164
	v_add_u32_e32 v167, v166, v164
	v_ashrrev_i32_e32 v164, 5, v167
	v_ashrrev_i32_e32 v165, 31, v164
	v_lshl_add_u64 v[164:165], s[38:39], 0, v[164:165]
	v_and_b32_e32 v167, 0xffffffe0, v167
	v_lshlrev_b64 v[164:165], 12, v[164:165]
	v_sub_u32_e32 v166, v166, v167
	v_lshl_add_u64 v[164:165], v[158:159], 0, v[164:165]
	v_ashrrev_i32_e32 v167, 31, v166
	v_lshl_add_u64 v[164:165], v[166:167], 1, v[164:165]
	s_cselect_b32 s99, 1, 0
	s_cmp_lg_u32 s4, 0
	s_cbranch_scc0 .Lwt_g3_p13
	global_store_dwordx4 v[164:165], v[160:163], off offset:2048 sc1
	s_branch .Lwt_g3_d13

.LBB0_643:
	s_waitcnt lgkmcnt(0)
	v_pk_mul_f32 v[188:189], v[56:57], v[140:141] op_sel_hi:[1,0]
	v_mov_b64_e32 v[56:57], 0
	v_pk_mul_f32 v[186:187], v[54:55], v[140:141] op_sel_hi:[1,0]
	v_mov_b64_e32 v[54:55], 0
	v_pk_mul_f32 v[190:191], v[52:53], v[140:141] op_sel_hi:[1,0]
	v_mov_b64_e32 v[52:53], 0
	v_pk_mul_f32 v[192:193], v[50:51], v[140:141] op_sel_hi:[1,0]
	v_mov_b64_e32 v[50:51], 0
	v_cvt_pk_bf16_f32 v186, v186, v187
	v_cvt_pk_bf16_f32 v187, v188, v189
	v_cvt_pk_bf16_f32 v188, v192, v193
	v_cvt_pk_bf16_f32 v189, v190, v191
	s_andn2_b64 vcc, exec, s[38:39]
	s_mov_b64 s[38:39], -1
	s_cselect_b32 s99, 1, 0
	s_cmp_lg_u32 s4, 0
	s_cbranch_scc0 .Lwt_g3_p14
	global_store_dwordx4 v[168:169], v[186:189], off sc1
	s_branch .Lwt_g3_d14

.LBB0_647:
	v_mov_b32_e32 v160, v140
	v_mov_b32_e32 v161, v140
	v_mov_b32_e32 v162, v140
	v_mov_b32_e32 v163, v140
	v_pk_mul_f32 v[164:165], v[24:25], v[162:163]
	v_mov_b64_e32 v[24:25], 0
	v_pk_mul_f32 v[166:167], v[22:23], v[160:161]
	v_mov_b64_e32 v[22:23], 0
	v_pk_mul_f32 v[186:187], v[20:21], v[162:163]
	v_mov_b64_e32 v[20:21], 0
	v_pk_mul_f32 v[162:163], v[18:19], v[160:161]
	v_mov_b64_e32 v[18:19], 0
	v_cvt_pk_bf16_f32 v160, v166, v167
	v_cvt_pk_bf16_f32 v161, v164, v165
	v_cvt_pk_bf16_f32 v162, v162, v163
	v_cvt_pk_bf16_f32 v163, v186, v187
	s_cselect_b32 s99, 1, 0
	s_cmp_lg_u32 s4, 0
	s_cbranch_scc0 .Lwt_g3_p15
	global_store_dwordx4 v[168:169], v[160:163], off sc1
	s_branch .Lwt_g3_d15

.LBB0_654:
	s_lshl_b32 s38, s57, 8
	s_and_b32 s38, s38, 0x300
	s_lshl_b32 s41, s14, 8
	s_waitcnt lgkmcnt(0)
	v_pk_mul_f32 v[160:161], v[126:127], v[146:147]
	v_mov_b64_e32 v[126:127], 0
	v_pk_mul_f32 v[162:163], v[128:129], v[148:149]
	v_mov_b64_e32 v[128:129], 0
	s_add_i32 s38, s38, s35
	s_lshl_b32 s39, s57, 2
	v_or_b32_e32 v166, s41, v181
	v_cvt_pk_bf16_f32 v160, v160, v161
	v_cvt_pk_bf16_f32 v161, v162, v163
	v_pk_mul_f32 v[162:163], v[122:123], v[150:151]
	v_mov_b64_e32 v[122:123], 0
	v_pk_mul_f32 v[164:165], v[124:125], v[152:153]
	v_mov_b64_e32 v[124:125], 0
	s_ashr_i32 s38, s38, 6
	s_and_b32 s39, s39, -16
	v_cvt_pk_bf16_f32 v162, v162, v163
	v_cvt_pk_bf16_f32 v163, v164, v165
	v_ashrrev_i32_e32 v164, 31, v166
	s_add_i32 s38, s39, s38
	v_lshrrev_b32_e32 v164, 27, v164
	s_addk_i32 s38, 0xff90
	v_add_u32_e32 v167, v166, v164
	s_ashr_i32 s39, s38, 31
	v_ashrrev_i32_e32 v164, 5, v167
	s_lshl_b64 s[38:39], s[38:39], 8
	v_ashrrev_i32_e32 v165, 31, v164
	v_lshl_add_u64 v[164:165], s[38:39], 0, v[164:165]
	v_and_b32_e32 v167, 0xffffffe0, v167
	v_lshlrev_b64 v[164:165], 12, v[164:165]
	v_sub_u32_e32 v166, v166, v167
	v_lshl_add_u64 v[164:165], v[158:159], 0, v[164:165]
	v_ashrrev_i32_e32 v167, 31, v166
	v_lshl_add_u64 v[164:165], v[166:167], 1, v[164:165]
	s_cselect_b32 s99, 1, 0
	s_cmp_lg_u32 s4, 0
	s_cbranch_scc0 .Lwt_g3_p16
	global_store_dwordx4 v[164:165], v[160:163], off offset:1024 sc1
	s_branch .Lwt_g3_d16

.Lwt_g3_d16:
	s_cmp_lg_u32 s99, 0
	v_or_b32_e32 v166, s41, v182
	v_pk_mul_f32 v[164:165], v[92:93], v[144:145]
	v_mov_b64_e32 v[92:93], 0
	v_pk_mul_f32 v[160:161], v[94:95], v[138:139]
	v_mov_b64_e32 v[94:95], 0
	v_pk_mul_f32 v[162:163], v[96:97], v[140:141]
	v_mov_b64_e32 v[96:97], 0
	v_cvt_pk_bf16_f32 v160, v160, v161
	v_cvt_pk_bf16_f32 v161, v162, v163
	v_pk_mul_f32 v[162:163], v[90:91], v[142:143]
	v_mov_b64_e32 v[90:91], 0
	s_nop 0
	v_cvt_pk_bf16_f32 v162, v162, v163
	v_cvt_pk_bf16_f32 v163, v164, v165
	v_ashrrev_i32_e32 v164, 31, v166
	v_lshrrev_b32_e32 v164, 27, v164
	v_add_u32_e32 v167, v166, v164
	v_ashrrev_i32_e32 v164, 5, v167
	v_ashrrev_i32_e32 v165, 31, v164
	v_lshl_add_u64 v[164:165], s[38:39], 0, v[164:165]
	v_and_b32_e32 v167, 0xffffffe0, v167
	v_lshlrev_b64 v[164:165], 12, v[164:165]
	v_sub_u32_e32 v166, v166, v167
	v_lshl_add_u64 v[164:165], v[158:159], 0, v[164:165]
	v_ashrrev_i32_e32 v167, 31, v166
	v_lshl_add_u64 v[164:165], v[166:167], 1, v[164:165]
	s_cselect_b32 s99, 1, 0
	s_cmp_lg_u32 s4, 0
	s_cbranch_scc0 .Lwt_g3_p17
	global_store_dwordx4 v[164:165], v[160:163], off offset:1024 sc1
	s_branch .Lwt_g3_d17

.LBB0_659:
	s_waitcnt lgkmcnt(0)
	v_pk_mul_f32 v[188:189], v[128:129], v[146:147] op_sel:[0,1]
	v_mov_b64_e32 v[128:129], 0
	v_pk_mul_f32 v[186:187], v[126:127], v[146:147] op_sel:[0,1]
	v_mov_b64_e32 v[126:127], 0
	v_pk_mul_f32 v[190:191], v[124:125], v[146:147] op_sel:[0,1]
	v_mov_b64_e32 v[124:125], 0
	v_pk_mul_f32 v[192:193], v[122:123], v[146:147] op_sel:[0,1]
	v_mov_b64_e32 v[122:123], 0
	v_cvt_pk_bf16_f32 v186, v186, v187
	v_cvt_pk_bf16_f32 v187, v188, v189
	v_cvt_pk_bf16_f32 v188, v192, v193
	v_cvt_pk_bf16_f32 v189, v190, v191
	s_andn2_b64 vcc, exec, s[38:39]
	s_mov_b64 s[38:39], -1
	s_cselect_b32 s99, 1, 0
	s_cmp_lg_u32 s4, 0
	s_cbranch_scc0 .Lwt_g3_p18
	global_store_dwordx4 v[168:169], v[186:189], off sc1
	s_branch .Lwt_g3_d18

.LBB0_663:
	v_mov_b32_e32 v160, v147
	v_mov_b32_e32 v161, v147
	v_mov_b32_e32 v162, v147
	v_mov_b32_e32 v163, v147
	v_pk_mul_f32 v[164:165], v[96:97], v[162:163]
	v_mov_b64_e32 v[96:97], 0
	v_pk_mul_f32 v[166:167], v[94:95], v[160:161]
	v_mov_b64_e32 v[94:95], 0
	v_pk_mul_f32 v[186:187], v[92:93], v[162:163]
	v_mov_b64_e32 v[92:93], 0
	v_pk_mul_f32 v[162:163], v[90:91], v[160:161]
	v_mov_b64_e32 v[90:91], 0
	v_cvt_pk_bf16_f32 v160, v166, v167
	v_cvt_pk_bf16_f32 v161, v164, v165
	v_cvt_pk_bf16_f32 v162, v162, v163
	v_cvt_pk_bf16_f32 v163, v186, v187
	s_cselect_b32 s99, 1, 0
	s_cmp_lg_u32 s4, 0
	s_cbranch_scc0 .Lwt_g3_p19
	global_store_dwordx4 v[168:169], v[160:163], off sc1
	s_branch .Lwt_g3_d19

.LBB0_666:
	s_lshl_b32 s38, s57, 8
	s_and_b32 s38, s38, 0x300
	s_lshl_b32 s41, s14, 8
	s_waitcnt lgkmcnt(0)
	v_pk_mul_f32 v[160:161], v[110:111], v[146:147]
	v_mov_b64_e32 v[110:111], 0
	v_pk_mul_f32 v[162:163], v[112:113], v[148:149]
	v_mov_b64_e32 v[112:113], 0
	s_add_i32 s38, s38, s35
	s_lshl_b32 s39, s57, 2
	v_or_b32_e32 v166, s41, v181
	v_cvt_pk_bf16_f32 v160, v160, v161
	v_cvt_pk_bf16_f32 v161, v162, v163
	v_pk_mul_f32 v[162:163], v[106:107], v[150:151]
	v_mov_b64_e32 v[106:107], 0
	v_pk_mul_f32 v[164:165], v[108:109], v[152:153]
	v_mov_b64_e32 v[108:109], 0
	s_ashr_i32 s38, s38, 6
	s_and_b32 s39, s39, -16
	v_cvt_pk_bf16_f32 v162, v162, v163
	v_cvt_pk_bf16_f32 v163, v164, v165
	v_ashrrev_i32_e32 v164, 31, v166
	s_add_i32 s38, s39, s38
	v_lshrrev_b32_e32 v164, 27, v164
	s_addk_i32 s38, 0xff90
	v_add_u32_e32 v167, v166, v164
	s_ashr_i32 s39, s38, 31
	v_ashrrev_i32_e32 v164, 5, v167
	s_lshl_b64 s[38:39], s[38:39], 8
	v_ashrrev_i32_e32 v165, 31, v164
	v_lshl_add_u64 v[164:165], s[38:39], 0, v[164:165]
	v_and_b32_e32 v167, 0xffffffe0, v167
	v_lshlrev_b64 v[164:165], 12, v[164:165]
	v_sub_u32_e32 v166, v166, v167
	v_lshl_add_u64 v[164:165], v[158:159], 0, v[164:165]
	v_ashrrev_i32_e32 v167, 31, v166
	v_lshl_add_u64 v[164:165], v[166:167], 1, v[164:165]
	s_cselect_b32 s99, 1, 0
	s_cmp_lg_u32 s4, 0
	s_cbranch_scc0 .Lwt_g3_p20
	global_store_dwordx4 v[164:165], v[160:163], off offset:3072 sc1
	s_branch .Lwt_g3_d20

.Lwt_g3_d20:
	s_cmp_lg_u32 s99, 0
	v_or_b32_e32 v166, s41, v182
	v_pk_mul_f32 v[164:165], v[76:77], v[144:145]
	v_mov_b64_e32 v[76:77], 0
	v_pk_mul_f32 v[160:161], v[78:79], v[138:139]
	v_mov_b64_e32 v[78:79], 0
	v_pk_mul_f32 v[162:163], v[80:81], v[140:141]
	v_mov_b64_e32 v[80:81], 0
	v_cvt_pk_bf16_f32 v160, v160, v161
	v_cvt_pk_bf16_f32 v161, v162, v163
	v_pk_mul_f32 v[162:163], v[74:75], v[142:143]
	v_mov_b64_e32 v[74:75], 0
	s_nop 0
	v_cvt_pk_bf16_f32 v162, v162, v163
	v_cvt_pk_bf16_f32 v163, v164, v165
	v_ashrrev_i32_e32 v164, 31, v166
	v_lshrrev_b32_e32 v164, 27, v164
	v_add_u32_e32 v167, v166, v164
	v_ashrrev_i32_e32 v164, 5, v167
	v_ashrrev_i32_e32 v165, 31, v164
	v_lshl_add_u64 v[164:165], s[38:39], 0, v[164:165]
	v_and_b32_e32 v167, 0xffffffe0, v167
	v_lshlrev_b64 v[164:165], 12, v[164:165]
	v_sub_u32_e32 v166, v166, v167
	v_lshl_add_u64 v[164:165], v[158:159], 0, v[164:165]
	v_ashrrev_i32_e32 v167, 31, v166
	v_lshl_add_u64 v[164:165], v[166:167], 1, v[164:165]
	s_cselect_b32 s99, 1, 0
	s_cmp_lg_u32 s4, 0
	s_cbranch_scc0 .Lwt_g3_p21
	global_store_dwordx4 v[164:165], v[160:163], off offset:3072 sc1
	s_branch .Lwt_g3_d21

.LBB0_671:
	s_waitcnt lgkmcnt(0)
	v_pk_mul_f32 v[188:189], v[112:113], v[148:149] op_sel:[0,1]
	v_mov_b64_e32 v[112:113], 0
	v_pk_mul_f32 v[186:187], v[110:111], v[148:149] op_sel:[0,1]
	v_mov_b64_e32 v[110:111], 0
	v_pk_mul_f32 v[190:191], v[108:109], v[148:149] op_sel:[0,1]
	v_mov_b64_e32 v[108:109], 0
	v_pk_mul_f32 v[192:193], v[106:107], v[148:149] op_sel:[0,1]
	v_mov_b64_e32 v[106:107], 0
	v_cvt_pk_bf16_f32 v186, v186, v187
	v_cvt_pk_bf16_f32 v187, v188, v189
	v_cvt_pk_bf16_f32 v188, v192, v193
	v_cvt_pk_bf16_f32 v189, v190, v191
	s_andn2_b64 vcc, exec, s[38:39]
	s_mov_b64 s[38:39], -1
	s_cselect_b32 s99, 1, 0
	s_cmp_lg_u32 s4, 0
	s_cbranch_scc0 .Lwt_g3_p22
	global_store_dwordx4 v[168:169], v[186:189], off sc1
	s_branch .Lwt_g3_d22

.LBB0_675:
	v_mov_b32_e32 v160, v149
	v_mov_b32_e32 v161, v149
	v_mov_b32_e32 v162, v149
	v_mov_b32_e32 v163, v149
	v_pk_mul_f32 v[164:165], v[80:81], v[162:163]
	v_mov_b64_e32 v[80:81], 0
	v_pk_mul_f32 v[166:167], v[78:79], v[160:161]
	v_mov_b64_e32 v[78:79], 0
	v_pk_mul_f32 v[186:187], v[76:77], v[162:163]
	v_mov_b64_e32 v[76:77], 0
	v_pk_mul_f32 v[162:163], v[74:75], v[160:161]
	v_mov_b64_e32 v[74:75], 0
	v_cvt_pk_bf16_f32 v160, v166, v167
	v_cvt_pk_bf16_f32 v161, v164, v165
	v_cvt_pk_bf16_f32 v162, v162, v163
	v_cvt_pk_bf16_f32 v163, v186, v187
	s_cselect_b32 s99, 1, 0
	s_cmp_lg_u32 s4, 0
	s_cbranch_scc0 .Lwt_g3_p23
	global_store_dwordx4 v[168:169], v[160:163], off sc1
	s_branch .Lwt_g3_d23

.LBB0_678:
	s_lshl_b32 s38, s57, 8
	s_and_b32 s38, s38, 0x300
	s_lshl_b32 s41, s14, 8
	s_waitcnt lgkmcnt(0)
	v_pk_mul_f32 v[160:161], v[62:63], v[146:147]
	v_mov_b64_e32 v[62:63], 0
	v_pk_mul_f32 v[162:163], v[64:65], v[148:149]
	v_mov_b64_e32 v[64:65], 0
	s_add_i32 s38, s38, s56
	s_lshl_b32 s39, s57, 2
	v_or_b32_e32 v166, s41, v181
	v_cvt_pk_bf16_f32 v160, v160, v161
	v_cvt_pk_bf16_f32 v161, v162, v163
	v_pk_mul_f32 v[162:163], v[58:59], v[150:151]
	v_mov_b64_e32 v[58:59], 0
	v_pk_mul_f32 v[164:165], v[60:61], v[152:153]
	v_mov_b64_e32 v[60:61], 0
	s_ashr_i32 s38, s38, 6
	s_and_b32 s39, s39, -16
	v_cvt_pk_bf16_f32 v162, v162, v163
	v_cvt_pk_bf16_f32 v163, v164, v165
	v_ashrrev_i32_e32 v164, 31, v166
	s_add_i32 s38, s39, s38
	v_lshrrev_b32_e32 v164, 27, v164
	s_addk_i32 s38, 0xff90
	v_add_u32_e32 v167, v166, v164
	s_ashr_i32 s39, s38, 31
	v_ashrrev_i32_e32 v164, 5, v167
	s_lshl_b64 s[38:39], s[38:39], 8
	v_ashrrev_i32_e32 v165, 31, v164
	v_lshl_add_u64 v[164:165], s[38:39], 0, v[164:165]
	v_and_b32_e32 v167, 0xffffffe0, v167
	v_lshlrev_b64 v[164:165], 12, v[164:165]
	v_sub_u32_e32 v166, v166, v167
	v_lshl_add_u64 v[164:165], v[158:159], 0, v[164:165]
	v_ashrrev_i32_e32 v167, 31, v166
	v_lshl_add_u64 v[164:165], v[166:167], 1, v[164:165]
	s_cselect_b32 s99, 1, 0
	s_cmp_lg_u32 s4, 0
	s_cbranch_scc0 .Lwt_g3_p24
	global_store_dwordx4 v[164:165], v[160:163], off offset:1024 sc1
	s_branch .Lwt_g3_d24

.Lwt_g3_d24:
	s_cmp_lg_u32 s99, 0
	v_or_b32_e32 v166, s41, v182
	v_pk_mul_f32 v[164:165], v[28:29], v[144:145]
	v_mov_b64_e32 v[28:29], 0
	v_pk_mul_f32 v[160:161], v[30:31], v[138:139]
	v_mov_b64_e32 v[30:31], 0
	v_pk_mul_f32 v[162:163], v[32:33], v[140:141]
	v_mov_b64_e32 v[32:33], 0
	v_cvt_pk_bf16_f32 v160, v160, v161
	v_cvt_pk_bf16_f32 v161, v162, v163
	v_pk_mul_f32 v[162:163], v[26:27], v[142:143]
	v_mov_b64_e32 v[26:27], 0
	s_nop 0
	v_cvt_pk_bf16_f32 v162, v162, v163
	v_cvt_pk_bf16_f32 v163, v164, v165
	v_ashrrev_i32_e32 v164, 31, v166
	v_lshrrev_b32_e32 v164, 27, v164
	v_add_u32_e32 v167, v166, v164
	v_ashrrev_i32_e32 v164, 5, v167
	v_ashrrev_i32_e32 v165, 31, v164
	v_lshl_add_u64 v[164:165], s[38:39], 0, v[164:165]
	v_and_b32_e32 v167, 0xffffffe0, v167
	v_lshlrev_b64 v[164:165], 12, v[164:165]
	v_sub_u32_e32 v166, v166, v167
	v_lshl_add_u64 v[164:165], v[158:159], 0, v[164:165]
	v_ashrrev_i32_e32 v167, 31, v166
	v_lshl_add_u64 v[164:165], v[166:167], 1, v[164:165]
	s_cselect_b32 s99, 1, 0
	s_cmp_lg_u32 s4, 0
	s_cbranch_scc0 .Lwt_g3_p25
	global_store_dwordx4 v[164:165], v[160:163], off offset:1024 sc1
	s_branch .Lwt_g3_d25

.LBB0_683:
	s_waitcnt lgkmcnt(0)
	v_pk_mul_f32 v[188:189], v[64:65], v[138:139] op_sel:[0,1]
	v_mov_b64_e32 v[64:65], 0
	v_pk_mul_f32 v[186:187], v[62:63], v[138:139] op_sel:[0,1]
	v_mov_b64_e32 v[62:63], 0
	v_pk_mul_f32 v[190:191], v[60:61], v[138:139] op_sel:[0,1]
	v_mov_b64_e32 v[60:61], 0
	v_pk_mul_f32 v[192:193], v[58:59], v[138:139] op_sel:[0,1]
	v_mov_b64_e32 v[58:59], 0
	v_cvt_pk_bf16_f32 v186, v186, v187
	v_cvt_pk_bf16_f32 v187, v188, v189
	v_cvt_pk_bf16_f32 v188, v192, v193
	v_cvt_pk_bf16_f32 v189, v190, v191
	s_andn2_b64 vcc, exec, s[38:39]
	s_mov_b64 s[38:39], -1
	s_cselect_b32 s99, 1, 0
	s_cmp_lg_u32 s4, 0
	s_cbranch_scc0 .Lwt_g3_p26
	global_store_dwordx4 v[168:169], v[186:189], off sc1
	s_branch .Lwt_g3_d26

.LBB0_687:
	v_mov_b32_e32 v160, v139
	v_mov_b32_e32 v161, v139
	v_mov_b32_e32 v162, v139
	v_mov_b32_e32 v163, v139
	v_pk_mul_f32 v[164:165], v[32:33], v[162:163]
	v_mov_b64_e32 v[32:33], 0
	v_pk_mul_f32 v[166:167], v[30:31], v[160:161]
	v_mov_b64_e32 v[30:31], 0
	v_pk_mul_f32 v[186:187], v[28:29], v[162:163]
	v_mov_b64_e32 v[28:29], 0
	v_pk_mul_f32 v[162:163], v[26:27], v[160:161]
	v_mov_b64_e32 v[26:27], 0
	v_cvt_pk_bf16_f32 v160, v166, v167
	v_cvt_pk_bf16_f32 v161, v164, v165
	v_cvt_pk_bf16_f32 v162, v162, v163
	v_cvt_pk_bf16_f32 v163, v186, v187
	s_cselect_b32 s99, 1, 0
	s_cmp_lg_u32 s4, 0
	s_cbranch_scc0 .Lwt_g3_p27
	global_store_dwordx4 v[168:169], v[160:163], off sc1
	s_branch .Lwt_g3_d27

.LBB0_690:
	s_lshl_b32 s8, s57, 8
	s_and_b32 s8, s8, 0x300
	s_lshl_b32 s38, s14, 8
	s_waitcnt lgkmcnt(0)
	v_pk_mul_f32 v[146:147], v[46:47], v[146:147]
	v_mov_b64_e32 v[46:47], 0
	v_pk_mul_f32 v[148:149], v[48:49], v[148:149]
	v_mov_b64_e32 v[48:49], 0
	s_add_i32 s8, s8, s56
	s_lshl_b32 s9, s57, 2
	v_or_b32_e32 v160, s38, v181
	v_cvt_pk_bf16_f32 v146, v146, v147
	v_cvt_pk_bf16_f32 v147, v148, v149
	v_pk_mul_f32 v[148:149], v[42:43], v[150:151]
	v_mov_b64_e32 v[42:43], 0
	v_pk_mul_f32 v[150:151], v[44:45], v[152:153]
	v_mov_b64_e32 v[44:45], 0
	s_ashr_i32 s8, s8, 6
	s_and_b32 s9, s9, -16
	v_cvt_pk_bf16_f32 v148, v148, v149
	v_cvt_pk_bf16_f32 v149, v150, v151
	v_ashrrev_i32_e32 v150, 31, v160
	s_add_i32 s8, s9, s8
	v_lshrrev_b32_e32 v150, 27, v150
	s_addk_i32 s8, 0xff90
	v_add_u32_e32 v152, v160, v150
	s_ashr_i32 s9, s8, 31
	v_ashrrev_i32_e32 v150, 5, v152
	s_lshl_b64 s[8:9], s[8:9], 8
	v_ashrrev_i32_e32 v151, 31, v150
	v_lshl_add_u64 v[150:151], s[8:9], 0, v[150:151]
	v_and_b32_e32 v152, 0xffffffe0, v152
	v_lshlrev_b64 v[150:151], 12, v[150:151]
	v_sub_u32_e32 v152, v160, v152
	v_lshl_add_u64 v[150:151], v[158:159], 0, v[150:151]
	v_ashrrev_i32_e32 v153, 31, v152
	v_lshl_add_u64 v[150:151], v[152:153], 1, v[150:151]
	v_pk_mul_f32 v[138:139], v[14:15], v[138:139]
	v_mov_b64_e32 v[14:15], 0
	s_cselect_b32 s99, 1, 0
	s_cmp_lg_u32 s4, 0
	s_cbranch_scc0 .Lwt_g3_p28
	global_store_dwordx4 v[150:151], v[146:149], off offset:3072 sc1
	s_branch .Lwt_g3_d28

.Lwt_g3_d28:
	s_cmp_lg_u32 s99, 0
	v_or_b32_e32 v150, s38, v182
	s_nop 0
	v_cvt_pk_bf16_f32 v146, v138, v139
	v_pk_mul_f32 v[138:139], v[16:17], v[140:141]
	v_mov_b64_e32 v[16:17], 0
	s_nop 0
	v_cvt_pk_bf16_f32 v147, v138, v139
	v_pk_mul_f32 v[138:139], v[10:11], v[142:143]
	v_mov_b64_e32 v[10:11], 0
	s_nop 0
	v_cvt_pk_bf16_f32 v148, v138, v139
	v_pk_mul_f32 v[138:139], v[12:13], v[144:145]
	v_mov_b64_e32 v[12:13], 0
	s_nop 0
	v_cvt_pk_bf16_f32 v149, v138, v139
	v_ashrrev_i32_e32 v138, 31, v150
	v_lshrrev_b32_e32 v138, 27, v138
	v_add_u32_e32 v142, v150, v138
	v_ashrrev_i32_e32 v138, 5, v142
	v_ashrrev_i32_e32 v139, 31, v138
	v_lshl_add_u64 v[138:139], s[8:9], 0, v[138:139]
	v_and_b32_e32 v142, 0xffffffe0, v142
	v_lshlrev_b64 v[138:139], 12, v[138:139]
	v_sub_u32_e32 v142, v150, v142
	v_lshl_add_u64 v[138:139], v[158:159], 0, v[138:139]
	v_ashrrev_i32_e32 v143, 31, v142
	v_lshl_add_u64 v[138:139], v[142:143], 1, v[138:139]
	s_cselect_b32 s99, 1, 0
	s_cmp_lg_u32 s4, 0
	s_cbranch_scc0 .Lwt_g3_p29
	global_store_dwordx4 v[138:139], v[146:149], off offset:3072 sc1
	s_branch .Lwt_g3_d29

.LBB0_695:
	v_pk_mul_f32 v[152:153], v[48:49], v[140:141] op_sel:[0,1]
	v_mov_b64_e32 v[48:49], 0
	v_pk_mul_f32 v[150:151], v[46:47], v[140:141] op_sel:[0,1]
	v_mov_b64_e32 v[46:47], 0
	v_pk_mul_f32 v[160:161], v[44:45], v[140:141] op_sel:[0,1]
	v_mov_b64_e32 v[44:45], 0
	v_pk_mul_f32 v[162:163], v[42:43], v[140:141] op_sel:[0,1]
	v_mov_b64_e32 v[42:43], 0
	v_cvt_pk_bf16_f32 v150, v150, v151
	v_cvt_pk_bf16_f32 v151, v152, v153
	v_cvt_pk_bf16_f32 v152, v162, v163
	v_cvt_pk_bf16_f32 v153, v160, v161
	s_andn2_b64 vcc, exec, s[8:9]
	s_mov_b64 s[8:9], -1
	s_cselect_b32 s99, 1, 0
	s_cmp_lg_u32 s4, 0
	s_cbranch_scc0 .Lwt_g3_p30
	global_store_dwordx4 v[148:149], v[150:153], off sc1
	s_branch .Lwt_g3_d30

.LBB0_699:
	v_mov_b32_e32 v140, v141
	v_mov_b32_e32 v138, v141
	v_mov_b32_e32 v139, v141
	v_pk_mul_f32 v[142:143], v[16:17], v[138:139]
	v_mov_b64_e32 v[16:17], 0
	v_pk_mul_f32 v[144:145], v[14:15], v[140:141]
	v_mov_b64_e32 v[14:15], 0
	v_pk_mul_f32 v[146:147], v[12:13], v[138:139]
	v_mov_b64_e32 v[12:13], 0
	v_pk_mul_f32 v[140:141], v[10:11], v[140:141]
	v_mov_b64_e32 v[10:11], 0
	v_cvt_pk_bf16_f32 v138, v144, v145
	v_cvt_pk_bf16_f32 v139, v142, v143
	v_cvt_pk_bf16_f32 v140, v140, v141
	v_cvt_pk_bf16_f32 v141, v146, v147
	s_cselect_b32 s99, 1, 0
	s_cmp_lg_u32 s4, 0
	s_cbranch_scc0 .Lwt_g3_p31
	global_store_dwordx4 v[148:149], v[138:141], off sc1
	s_branch .Lwt_g3_d31

.Lprio_g4_done:
.LBB0_946:
	v_add_u32_e32 v164, s88, v150
	v_add_u32_e32 v180, s45, v150
	s_add_u32 s24, s8, s22
	ds_read_b128 v[152:155], v164
	ds_read_b128 v[156:159], v164 offset:1024
	ds_read_b128 v[160:163], v164 offset:2048
	ds_read_b128 v[164:167], v164 offset:3072
	ds_read_b128 v[168:171], v180
	ds_read_b128 v[172:175], v180 offset:1024
	ds_read_b128 v[176:179], v180 offset:2048
	ds_read_b128 v[180:183], v180 offset:3072
	s_addc_u32 s25, s9, s23
	s_add_u32 s24, s24, 0x100
	s_addc_u32 s25, s25, 0
	s_add_u32 s50, s13, s22
	s_addc_u32 s51, s48, s23
	s_cmpk_eq_i32 s22, 0x700
	s_cselect_b32 s27, s21, s25
	s_cselect_b32 s26, s20, s24
	s_cselect_b32 s25, s17, s51
	s_cselect_b32 s24, s16, s50
	v_lshl_add_u64 v[218:219], v[146:147], 0, s[22:23]
	s_add_i32 m0, s37, 0xc000
	ds_read_b128 v[184:187], v151
	ds_read_b128 v[190:193], v151 offset:1024
	ds_read_b128 v[194:197], v151 offset:2048
	ds_read_b128 v[198:201], v151 offset:3072
	ds_read_b128 v[202:205], v151 offset:4096
	ds_read_b128 v[206:209], v151 offset:5120
	ds_read_b128 v[210:213], v151 offset:6144
	ds_read_b128 v[214:217], v151 offset:7168
	global_load_lds_dwordx4 v[218:219], off
	v_lshl_add_u64 v[218:219], v[148:149], 0, s[22:23]
	s_add_i32 m0, s37, 0xe000
	s_nop 0
	global_load_lds_dwordx4 v[218:219], off
	s_waitcnt vmcnt(8)
	s_waitcnt lgkmcnt(0)
	s_barrier
	s_waitcnt lgkmcnt(0)
	v_mfma_f32_16x16x32_bf16 v[126:129], v[152:155], v[184:187], v[126:129]
	v_mfma_f32_16x16x32_bf16 v[122:125], v[160:163], v[184:187], v[122:125]
	v_mfma_f32_16x16x32_bf16 v[110:113], v[152:155], v[194:197], v[110:113]
	v_mfma_f32_16x16x32_bf16 v[106:109], v[160:163], v[194:197], v[106:109]
	v_mfma_f32_16x16x32_bf16 v[94:97], v[152:155], v[202:205], v[94:97]
	v_mfma_f32_16x16x32_bf16 v[90:93], v[160:163], v[202:205], v[90:93]
	v_mfma_f32_16x16x32_bf16 v[78:81], v[152:155], v[210:213], v[78:81]
	v_mfma_f32_16x16x32_bf16 v[74:77], v[160:163], v[210:213], v[74:77]
	v_mfma_f32_16x16x32_bf16 v[126:129], v[156:159], v[190:193], v[126:129]
	v_mfma_f32_16x16x32_bf16 v[122:125], v[164:167], v[190:193], v[122:125]
	v_mfma_f32_16x16x32_bf16 v[110:113], v[156:159], v[198:201], v[110:113]
	v_mfma_f32_16x16x32_bf16 v[106:109], v[164:167], v[198:201], v[106:109]
	v_mfma_f32_16x16x32_bf16 v[94:97], v[156:159], v[206:209], v[94:97]
	v_mfma_f32_16x16x32_bf16 v[90:93], v[164:167], v[206:209], v[90:93]
	v_mfma_f32_16x16x32_bf16 v[78:81], v[156:159], v[214:217], v[78:81]
	v_mfma_f32_16x16x32_bf16 v[74:77], v[164:167], v[214:217], v[74:77]
	v_mfma_f32_16x16x32_bf16 v[118:121], v[168:171], v[184:187], v[118:121]
	v_mfma_f32_16x16x32_bf16 v[114:117], v[176:179], v[184:187], v[114:117]
	v_mfma_f32_16x16x32_bf16 v[102:105], v[168:171], v[194:197], v[102:105]
	v_mfma_f32_16x16x32_bf16 v[98:101], v[176:179], v[194:197], v[98:101]
	v_mfma_f32_16x16x32_bf16 v[86:89], v[168:171], v[202:205], v[86:89]
	v_mfma_f32_16x16x32_bf16 v[82:85], v[176:179], v[202:205], v[82:85]
	v_mfma_f32_16x16x32_bf16 v[70:73], v[168:171], v[210:213], v[70:73]
	v_mfma_f32_16x16x32_bf16 v[66:69], v[176:179], v[210:213], v[66:69]
	v_mfma_f32_16x16x32_bf16 v[118:121], v[172:175], v[190:193], v[118:121]
	v_mfma_f32_16x16x32_bf16 v[114:117], v[180:183], v[190:193], v[114:117]
	v_mfma_f32_16x16x32_bf16 v[102:105], v[172:175], v[198:201], v[102:105]
	v_mfma_f32_16x16x32_bf16 v[98:101], v[180:183], v[198:201], v[98:101]
	v_mfma_f32_16x16x32_bf16 v[86:89], v[172:175], v[206:209], v[86:89]
	v_mfma_f32_16x16x32_bf16 v[82:85], v[180:183], v[206:209], v[82:85]
	v_mfma_f32_16x16x32_bf16 v[70:73], v[172:175], v[214:217], v[70:73]
	v_mfma_f32_16x16x32_bf16 v[66:69], v[180:183], v[214:217], v[66:69]
	s_barrier
	s_add_i32 s50, s88, s36
	v_lshl_add_u64 v[218:219], s[24:25], 0, v[130:131]
	s_mov_b32 m0, s50
	ds_read_b128 v[184:187], v151 offset:16384
	ds_read_b128 v[190:193], v151 offset:17408
	ds_read_b128 v[194:197], v151 offset:18432
	ds_read_b128 v[198:201], v151 offset:19456
	ds_read_b128 v[202:205], v151 offset:20480
	ds_read_b128 v[206:209], v151 offset:21504
	ds_read_b128 v[210:213], v151 offset:22528
	ds_read_b128 v[214:217], v151 offset:23552
	global_load_lds_dwordx4 v[218:219], off
	s_add_i32 m0, s50, 0x2000
	s_add_u32 s50, s24, 0x40000
	v_lshl_add_u64 v[220:221], s[24:25], 0, v[132:133]
	s_addc_u32 s51, s25, 0
	s_add_i32 s52, s45, s36
	global_load_lds_dwordx4 v[220:221], off
	v_lshl_add_u64 v[222:223], s[50:51], 0, v[130:131]
	s_mov_b32 m0, s52
	v_lshl_add_u64 v[224:225], s[26:27], 0, v[136:137]
	global_load_lds_dwordx4 v[222:223], off
	v_lshl_add_u64 v[222:223], s[50:51], 0, v[132:133]
	s_add_i32 m0, s52, 0x2000
	s_nop 0
	global_load_lds_dwordx4 v[222:223], off
	v_lshl_add_u64 v[222:223], s[26:27], 0, v[134:135]
	s_mov_b32 m0, s37
	s_nop 0
	global_load_lds_dwordx4 v[222:223], off
	s_mov_b32 m0, s38
	s_nop 0
	global_load_lds_dwordx4 v[224:225], off
	s_waitcnt vmcnt(8)
	s_waitcnt lgkmcnt(0)
	s_barrier
	s_waitcnt lgkmcnt(0)
	v_mfma_f32_16x16x32_bf16 v[62:65], v[152:155], v[184:187], v[62:65]
	v_mfma_f32_16x16x32_bf16 v[58:61], v[160:163], v[184:187], v[58:61]
	v_mfma_f32_16x16x32_bf16 v[46:49], v[152:155], v[194:197], v[46:49]
	v_mfma_f32_16x16x32_bf16 v[42:45], v[160:163], v[194:197], v[42:45]
	v_mfma_f32_16x16x32_bf16 v[30:33], v[152:155], v[202:205], v[30:33]
	v_mfma_f32_16x16x32_bf16 v[26:29], v[160:163], v[202:205], v[26:29]
	v_mfma_f32_16x16x32_bf16 v[14:17], v[152:155], v[210:213], v[14:17]
	v_mfma_f32_16x16x32_bf16 v[10:13], v[160:163], v[210:213], v[10:13]
	v_mfma_f32_16x16x32_bf16 v[62:65], v[156:159], v[190:193], v[62:65]
	v_mfma_f32_16x16x32_bf16 v[58:61], v[164:167], v[190:193], v[58:61]
	v_mfma_f32_16x16x32_bf16 v[46:49], v[156:159], v[198:201], v[46:49]
	v_mfma_f32_16x16x32_bf16 v[42:45], v[164:167], v[198:201], v[42:45]
	v_mfma_f32_16x16x32_bf16 v[30:33], v[156:159], v[206:209], v[30:33]
	v_mfma_f32_16x16x32_bf16 v[26:29], v[164:167], v[206:209], v[26:29]
	v_mfma_f32_16x16x32_bf16 v[14:17], v[156:159], v[214:217], v[14:17]
	v_mfma_f32_16x16x32_bf16 v[10:13], v[164:167], v[214:217], v[10:13]
	v_mfma_f32_16x16x32_bf16 v[54:57], v[168:171], v[184:187], v[54:57]
	v_mfma_f32_16x16x32_bf16 v[50:53], v[176:179], v[184:187], v[50:53]
	v_mfma_f32_16x16x32_bf16 v[38:41], v[168:171], v[194:197], v[38:41]
	v_mfma_f32_16x16x32_bf16 v[34:37], v[176:179], v[194:197], v[34:37]
	v_mfma_f32_16x16x32_bf16 v[22:25], v[168:171], v[202:205], v[22:25]
	v_mfma_f32_16x16x32_bf16 v[18:21], v[176:179], v[202:205], v[18:21]
	v_mfma_f32_16x16x32_bf16 v[6:9], v[168:171], v[210:213], v[6:9]
	v_mfma_f32_16x16x32_bf16 v[2:5], v[176:179], v[210:213], v[2:5]
	v_mfma_f32_16x16x32_bf16 v[54:57], v[172:175], v[190:193], v[54:57]
	v_mfma_f32_16x16x32_bf16 v[50:53], v[180:183], v[190:193], v[50:53]
	v_mfma_f32_16x16x32_bf16 v[38:41], v[172:175], v[198:201], v[38:41]
	v_mfma_f32_16x16x32_bf16 v[34:37], v[180:183], v[198:201], v[34:37]
	v_mfma_f32_16x16x32_bf16 v[22:25], v[172:175], v[206:209], v[22:25]
	v_mfma_f32_16x16x32_bf16 v[18:21], v[180:183], v[206:209], v[18:21]
	v_mfma_f32_16x16x32_bf16 v[6:9], v[172:175], v[214:217], v[6:9]
	v_mfma_f32_16x16x32_bf16 v[2:5], v[180:183], v[214:217], v[2:5]
	s_barrier
	s_add_i32 s50, 0, 0x18000
	s_add_i32 s51, 0, 0x1c000
	v_add_u32_e32 v164, s50, v150
	v_add_u32_e32 v180, s51, v150
	ds_read_b128 v[152:155], v164
	ds_read_b128 v[156:159], v164 offset:1024
	ds_read_b128 v[160:163], v164 offset:2048
	ds_read_b128 v[164:167], v164 offset:3072
	ds_read_b128 v[168:171], v180
	ds_read_b128 v[172:175], v180 offset:1024
	ds_read_b128 v[176:179], v180 offset:2048
	ds_read_b128 v[180:183], v180 offset:3072
	s_add_u32 s26, s26, 0x40000
	s_addc_u32 s27, s27, 0
	s_mov_b32 m0, s39
	v_lshl_add_u64 v[226:227], s[26:27], 0, v[134:135]
	ds_read_b128 v[184:187], v151 offset:32768
	ds_read_b128 v[190:193], v151 offset:33792
	ds_read_b128 v[194:197], v151 offset:34816
	ds_read_b128 v[198:201], v151 offset:35840
	ds_read_b128 v[202:205], v151 offset:36864
	ds_read_b128 v[206:209], v151 offset:37888
	ds_read_b128 v[210:213], v151 offset:38912
	ds_read_b128 v[214:217], v151 offset:39936
	global_load_lds_dwordx4 v[226:227], off
	v_lshl_add_u64 v[226:227], s[26:27], 0, v[136:137]
	s_mov_b32 m0, s41
	s_nop 0
	global_load_lds_dwordx4 v[226:227], off
	s_waitcnt vmcnt(8)
	s_waitcnt lgkmcnt(0)
	s_barrier
	s_waitcnt lgkmcnt(0)
	v_mfma_f32_16x16x32_bf16 v[126:129], v[152:155], v[184:187], v[126:129]
	v_mfma_f32_16x16x32_bf16 v[122:125], v[160:163], v[184:187], v[122:125]
	v_mfma_f32_16x16x32_bf16 v[110:113], v[152:155], v[194:197], v[110:113]
	v_mfma_f32_16x16x32_bf16 v[106:109], v[160:163], v[194:197], v[106:109]
	v_mfma_f32_16x16x32_bf16 v[94:97], v[152:155], v[202:205], v[94:97]
	v_mfma_f32_16x16x32_bf16 v[90:93], v[160:163], v[202:205], v[90:93]
	v_mfma_f32_16x16x32_bf16 v[78:81], v[152:155], v[210:213], v[78:81]
	v_mfma_f32_16x16x32_bf16 v[74:77], v[160:163], v[210:213], v[74:77]
	v_mfma_f32_16x16x32_bf16 v[126:129], v[156:159], v[190:193], v[126:129]
	v_mfma_f32_16x16x32_bf16 v[122:125], v[164:167], v[190:193], v[122:125]
	v_mfma_f32_16x16x32_bf16 v[110:113], v[156:159], v[198:201], v[110:113]
	v_mfma_f32_16x16x32_bf16 v[106:109], v[164:167], v[198:201], v[106:109]
	v_mfma_f32_16x16x32_bf16 v[94:97], v[156:159], v[206:209], v[94:97]
	v_mfma_f32_16x16x32_bf16 v[90:93], v[164:167], v[206:209], v[90:93]
	v_mfma_f32_16x16x32_bf16 v[78:81], v[156:159], v[214:217], v[78:81]
	v_mfma_f32_16x16x32_bf16 v[74:77], v[164:167], v[214:217], v[74:77]
	v_mfma_f32_16x16x32_bf16 v[118:121], v[168:171], v[184:187], v[118:121]
	v_mfma_f32_16x16x32_bf16 v[114:117], v[176:179], v[184:187], v[114:117]
	v_mfma_f32_16x16x32_bf16 v[102:105], v[168:171], v[194:197], v[102:105]
	v_mfma_f32_16x16x32_bf16 v[98:101], v[176:179], v[194:197], v[98:101]
	v_mfma_f32_16x16x32_bf16 v[86:89], v[168:171], v[202:205], v[86:89]
	v_mfma_f32_16x16x32_bf16 v[82:85], v[176:179], v[202:205], v[82:85]
	v_mfma_f32_16x16x32_bf16 v[70:73], v[168:171], v[210:213], v[70:73]
	v_mfma_f32_16x16x32_bf16 v[66:69], v[176:179], v[210:213], v[66:69]
	v_mfma_f32_16x16x32_bf16 v[118:121], v[172:175], v[190:193], v[118:121]
	v_mfma_f32_16x16x32_bf16 v[114:117], v[180:183], v[190:193], v[114:117]
	v_mfma_f32_16x16x32_bf16 v[102:105], v[172:175], v[198:201], v[102:105]
	v_mfma_f32_16x16x32_bf16 v[98:101], v[180:183], v[198:201], v[98:101]
	v_mfma_f32_16x16x32_bf16 v[86:89], v[172:175], v[206:209], v[86:89]
	v_mfma_f32_16x16x32_bf16 v[82:85], v[180:183], v[206:209], v[82:85]
	v_mfma_f32_16x16x32_bf16 v[70:73], v[172:175], v[214:217], v[70:73]
	v_mfma_f32_16x16x32_bf16 v[66:69], v[180:183], v[214:217], v[66:69]
	s_barrier
	s_add_i32 s26, s50, s36
	v_lshl_add_u64 v[218:219], v[218:219], 0, s[10:11]
	s_mov_b32 m0, s26
	ds_read_b128 v[184:187], v151 offset:49152
	ds_read_b128 v[190:193], v151 offset:50176
	ds_read_b128 v[194:197], v151 offset:51200
	ds_read_b128 v[198:201], v151 offset:52224
	ds_read_b128 v[202:205], v151 offset:53248
	ds_read_b128 v[206:209], v151 offset:54272
	ds_read_b128 v[210:213], v151 offset:55296
	ds_read_b128 v[214:217], v151 offset:56320
	global_load_lds_dwordx4 v[218:219], off
	s_add_i32 m0, s26, 0x2000
	s_add_u32 s24, s24, 0x40080
	v_lshl_add_u64 v[218:219], v[220:221], 0, s[10:11]
	s_addc_u32 s25, s25, 0
	s_add_i32 s26, s51, s36
	global_load_lds_dwordx4 v[218:219], off
	v_lshl_add_u64 v[218:219], s[24:25], 0, v[130:131]
	s_mov_b32 m0, s26
	s_nop 0
	global_load_lds_dwordx4 v[218:219], off
	v_lshl_add_u64 v[218:219], s[24:25], 0, v[132:133]
	s_add_i32 m0, s26, 0x2000
	s_nop 0
	global_load_lds_dwordx4 v[218:219], off
	v_lshl_add_u64 v[218:219], v[222:223], 0, s[10:11]
	s_mov_b32 m0, s42
	s_nop 0
	global_load_lds_dwordx4 v[218:219], off
	v_lshl_add_u64 v[218:219], v[224:225], 0, s[10:11]
	s_mov_b32 m0, s43
	s_nop 0
	global_load_lds_dwordx4 v[218:219], off
	s_waitcnt vmcnt(8)
	s_waitcnt lgkmcnt(0)
	s_barrier
	s_waitcnt lgkmcnt(0)
	v_mfma_f32_16x16x32_bf16 v[62:65], v[152:155], v[184:187], v[62:65]
	v_mfma_f32_16x16x32_bf16 v[58:61], v[160:163], v[184:187], v[58:61]
	v_mfma_f32_16x16x32_bf16 v[46:49], v[152:155], v[194:197], v[46:49]
	v_mfma_f32_16x16x32_bf16 v[42:45], v[160:163], v[194:197], v[42:45]
	v_mfma_f32_16x16x32_bf16 v[30:33], v[152:155], v[202:205], v[30:33]
	v_mfma_f32_16x16x32_bf16 v[26:29], v[160:163], v[202:205], v[26:29]
	v_mfma_f32_16x16x32_bf16 v[14:17], v[152:155], v[210:213], v[14:17]
	v_mfma_f32_16x16x32_bf16 v[10:13], v[160:163], v[210:213], v[10:13]
	v_mfma_f32_16x16x32_bf16 v[62:65], v[156:159], v[190:193], v[62:65]
	v_mfma_f32_16x16x32_bf16 v[58:61], v[164:167], v[190:193], v[58:61]
	v_mfma_f32_16x16x32_bf16 v[46:49], v[156:159], v[198:201], v[46:49]
	v_mfma_f32_16x16x32_bf16 v[42:45], v[164:167], v[198:201], v[42:45]
	v_mfma_f32_16x16x32_bf16 v[30:33], v[156:159], v[206:209], v[30:33]
	v_mfma_f32_16x16x32_bf16 v[26:29], v[164:167], v[206:209], v[26:29]
	v_mfma_f32_16x16x32_bf16 v[14:17], v[156:159], v[214:217], v[14:17]
	v_mfma_f32_16x16x32_bf16 v[10:13], v[164:167], v[214:217], v[10:13]
	v_mfma_f32_16x16x32_bf16 v[54:57], v[168:171], v[184:187], v[54:57]
	v_mfma_f32_16x16x32_bf16 v[50:53], v[176:179], v[184:187], v[50:53]
	v_mfma_f32_16x16x32_bf16 v[38:41], v[168:171], v[194:197], v[38:41]
	v_mfma_f32_16x16x32_bf16 v[34:37], v[176:179], v[194:197], v[34:37]
	v_mfma_f32_16x16x32_bf16 v[22:25], v[168:171], v[202:205], v[22:25]
	v_mfma_f32_16x16x32_bf16 v[18:21], v[176:179], v[202:205], v[18:21]
	v_mfma_f32_16x16x32_bf16 v[6:9], v[168:171], v[210:213], v[6:9]
	v_mfma_f32_16x16x32_bf16 v[2:5], v[176:179], v[210:213], v[2:5]
	v_mfma_f32_16x16x32_bf16 v[54:57], v[172:175], v[190:193], v[54:57]
	v_mfma_f32_16x16x32_bf16 v[50:53], v[180:183], v[190:193], v[50:53]
	v_mfma_f32_16x16x32_bf16 v[38:41], v[172:175], v[198:201], v[38:41]
	v_mfma_f32_16x16x32_bf16 v[34:37], v[180:183], v[198:201], v[34:37]
	v_mfma_f32_16x16x32_bf16 v[22:25], v[172:175], v[206:209], v[22:25]
	v_mfma_f32_16x16x32_bf16 v[18:21], v[180:183], v[206:209], v[18:21]
	v_mfma_f32_16x16x32_bf16 v[6:9], v[172:175], v[214:217], v[6:9]
	v_mfma_f32_16x16x32_bf16 v[2:5], v[180:183], v[214:217], v[2:5]
	s_barrier
	s_add_i32 s49, s49, 2
	s_add_u32 s22, s22, 0x100
	s_addc_u32 s23, s23, 0
	s_cmp_gt_u32 s49, 13
	s_cbranch_scc0 .LBB0_946
	s_setprio 0
	s_add_u32 s22, s13, 0xffffff00
	s_addc_u32 s23, s48, -1
	s_andn2_b64 vcc, exec, s[4:5]
	s_cbranch_vccnz .LBB0_937
	v_mov_b32_e32 v2, 0
	s_mov_b32 s18, s46
	s_mov_b32 s6, s12
	s_mov_b64 s[8:9], s[20:21]
	s_mov_b32 s44, s47
	v_mov_b32_e32 v3, 0
	v_mov_b64_e32 v[4:5], 0
	v_mov_b64_e32 v[6:7], 0
	v_mov_b64_e32 v[8:9], 0
	v_mov_b64_e32 v[10:11], 0
	v_mov_b64_e32 v[12:13], 0
	v_mov_b64_e32 v[14:15], 0
	v_mov_b64_e32 v[16:17], 0
	v_mov_b64_e32 v[18:19], 0
	v_mov_b64_e32 v[20:21], 0
	v_mov_b64_e32 v[22:23], 0
	v_mov_b64_e32 v[24:25], 0
	v_mov_b64_e32 v[26:27], 0
	v_mov_b64_e32 v[28:29], 0
	v_mov_b64_e32 v[30:31], 0
	v_mov_b64_e32 v[32:33], 0
	v_mov_b64_e32 v[34:35], 0
	v_mov_b64_e32 v[36:37], 0
	v_mov_b64_e32 v[38:39], 0
	v_mov_b64_e32 v[40:41], 0
	v_mov_b64_e32 v[42:43], 0
	v_mov_b64_e32 v[44:45], 0
	v_mov_b64_e32 v[46:47], 0
	v_mov_b64_e32 v[48:49], 0
	v_mov_b64_e32 v[50:51], 0
	v_mov_b64_e32 v[52:53], 0
	v_mov_b64_e32 v[54:55], 0
	v_mov_b64_e32 v[56:57], 0
	v_mov_b64_e32 v[58:59], 0
	v_mov_b64_e32 v[60:61], 0
	v_mov_b64_e32 v[62:63], 0
	v_mov_b64_e32 v[64:65], 0
	v_mov_b64_e32 v[66:67], 0
	v_mov_b64_e32 v[68:69], 0
	v_mov_b64_e32 v[70:71], 0
	v_mov_b64_e32 v[72:73], 0
	v_mov_b64_e32 v[74:75], 0
	v_mov_b64_e32 v[76:77], 0
	v_mov_b64_e32 v[78:79], 0
	v_mov_b64_e32 v[80:81], 0
	v_mov_b64_e32 v[82:83], 0
	v_mov_b64_e32 v[84:85], 0
	v_mov_b64_e32 v[86:87], 0
	v_mov_b64_e32 v[88:89], 0
	v_mov_b64_e32 v[90:91], 0
	v_mov_b64_e32 v[92:93], 0
	v_mov_b64_e32 v[94:95], 0
	v_mov_b64_e32 v[96:97], 0
	v_mov_b64_e32 v[98:99], 0
	v_mov_b64_e32 v[100:101], 0
	v_mov_b64_e32 v[102:103], 0
	v_mov_b64_e32 v[104:105], 0
	v_mov_b64_e32 v[106:107], 0
	v_mov_b64_e32 v[108:109], 0
	v_mov_b64_e32 v[110:111], 0
	v_mov_b64_e32 v[112:113], 0
	v_mov_b64_e32 v[114:115], 0
	v_mov_b64_e32 v[116:117], 0
	v_mov_b64_e32 v[118:119], 0
	v_mov_b64_e32 v[120:121], 0
	v_mov_b64_e32 v[122:123], 0
	v_mov_b64_e32 v[124:125], 0
	v_mov_b64_e32 v[126:127], 0
	v_mov_b64_e32 v[128:129], 0
	s_andn2_b64 vcc, exec, s[0:1]
	s_cbranch_vccnz .LBB0_938
